# SwiGLU phases on 240 WGs (still 6 rounds); WGs 240-255 convert weights during the whole phase, 208-239 during the last round (same arrays as v54)
# speedup vs baseline: 1.0071x; 1.0071x over previous
; #define PG8_STAGE(bufoff, gbase, voff) do { _Pragma("unroll") for (int _i = 0; _i < 2; ++_i) \
;         __builtin_amdgcn_global_load_lds((const unsigned*)((const char*)(gbase) + (voff)[_i]), (LAS unsigned*)(lds + (bufoff) + ldsw + _i * 8192), 16, 0, 0); } while (0)
; #define PG8_WAIT_V(n) asm volatile("s_waitcnt vmcnt(" #n ")" ::: "memory")
; #define PG8_BAR __builtin_amdgcn_s_barrier()
; template <class Epi>
; __device__ __forceinline__ void gemm_phase(LAS unsigned char* lds, const Gemm g, const StaticOrder& S, const Epi& E, const int tid) {
;     const int wid = __builtin_amdgcn_readfirstlane(tid >> 6), lane = tid & 63, wr = wid >> 2, wc = wid & 3, fr = lane & 15, fq = lane >> 4;
;     int K_ = g.K; asm volatile("" : "+s"(K_));
;     const int K = K_, nt = K / BK;
;     unsigned voffA[2], voffB[2];
; #pragma unroll
;     for (int i = 0; i < 2; ++i) { int R, C; stage_rc(tid * 16 + i * 8192, R, C); const int Rb = Epi::PERM ? ((R & ~31) + perm32(R & 31)) : R;
;         voffA[i] = (unsigned)(R * g.lda + C) * 2u; voffB[i] = (unsigned)(Rb * g.ldb + C) * 2u; }
;     const size_t kstep = (size_t)(BK * 2);
;     const size_t hstepA = (size_t)HALF * g.lda * 2, hstepB = (size_t)HALF * g.ldb * 2;
;     const size_t tstepA = 2 * hstepA, tstepB = 2 * hstepB;
;     const unsigned ldsw = (unsigned)wid * 1024u;
;     const int aoff = lds_byte(wr * 64 + fr, fq * 8), boff = lds_byte(wc * 32 + fr, fq * 8);
;     ...
;     Unit cur, nxt; int ui = 0;
;     if (!S.next(0, cur)) return;
;     f32x4 acc[2][2][4][2];
; #pragma unroll
;     for (int a = 0; a < 2; ++a)
; #pragma unroll
;         for (int b = 0; b < 2; ++b)
; #pragma unroll
;             for (int m = 0; m < 4; ++m)
; #pragma unroll
;                 for (int n = 0; n < 2; ++n) acc[a][b][m][n] = (f32x4){0.f, 0.f, 0.f, 0.f};
;     bf16x8 At[4][2], B0[2][2], B1[2][2];
;     const char* cA = PG8_APTR(cur); const char* cB = PG8_BPTR(cur);
;     PG8_STAGE(PG8_SB(0, 0), cB, voffB); PG8_STAGE(PG8_SB(0, 1), cB + hstepB, voffB); PG8_STAGE(PG8_SA(0, 0), cA, voffA); PG8_STAGE(PG8_SA(0, 1), cA + hstepA, voffA);
;     if (wr == 1) PG8_BAR;
;     PG8_WAIT_V(2); PG8_BAR;
;     PG8_STAGE(PG8_SB(1, 0), cB + kstep, voffB); PG8_STAGE(PG8_SA(1, 0), cA + kstep, voffA); PG8_STAGE(PG8_SB(1, 1), cB + hstepB + kstep, voffB);
;     PG8_WAIT_V(6); PG8_BAR;
.LBB0_401:
	v_readlane_b32 s0, v254, 63
	v_readlane_b32 s1, v255, 0
	s_and_b64 vcc, exec, s[0:1]
	s_cbranch_vccz .LBB0_419
	v_readfirstlane_b32 s7, v212
	s_movk_i32 s10, 0x800
	s_cmpk_gt_i32 s94, 0x57f
	s_cbranch_scc1 .LBB0_419
	v_readlane_b32 s59, v255, 5
	s_cmpk_lg_i32 s59, 0x100
	s_cbranch_scc1 .Lded_no
	s_cmpk_gt_i32 s94, 0xef
	s_cbranch_scc1 .LBB0_418
.Lded_no:
	v_lshlrev_b32_e32 v1, 4, v212
	v_add_u32_e32 v2, 0x2000, v1
	s_waitcnt lgkmcnt(0)
	v_ashrrev_i32_e32 v3, 31, v2
	v_lshrrev_b32_e32 v3, 22, v3
	v_add_u32_e32 v3, v2, v3
	v_ashrrev_i32_e32 v10, 10, v3
	v_mul_i32_i24_e32 v3, 0x400, v10
	v_sub_u32_e32 v2, v2, v3
	v_lshrrev_b32_e32 v3, 4, v2
	v_bitop3_b32 v2, v3, v2, 32 bitop3:0x6c
	v_readlane_b32 s0, v254, 30
	v_ashrrev_i32_e32 v3, 31, v2
	s_add_u32 s36, s38, s0
	v_lshrrev_b32_e32 v3, 26, v3
	s_addc_u32 s37, s39, 0
	v_add_u32_e32 v3, v2, v3
	v_lshlrev_b32_e32 v4, 3, v10
	s_ashr_i32 s39, s94, 31
	v_ashrrev_i32_e32 v11, 6, v3
	v_and_b32_e32 v4, -16, v4
	s_lshr_b32 s0, s39, 29
	v_add_u32_e32 v4, v11, v4
	s_add_i32 s0, s94, s0
	s_ashr_i32 s16, s7, 6
	v_and_b32_e32 v5, 3, v11
	v_lshrrev_b32_e32 v6, 2, v4
	v_lshlrev_b32_e32 v7, 1, v4
	v_and_b32_e32 v3, 0xc0, v3
	s_ashr_i32 s1, s0, 3
	s_and_b32 s0, s0, -8
	s_ashr_i32 s11, s7, 8
	s_lshl_b32 s38, s16, 10
	v_and_or_b32 v5, v4, s89, v5
	v_and_b32_e32 v6, 4, v6
	v_and_b32_e32 v7, 24, v7
	v_sub_u32_e32 v2, v2, v3
	s_sub_i32 s0, s94, s0
	v_or3_b32 v5, v5, v6, v7
	v_lshlrev_b32_e32 v6, 5, v10
	v_ashrrev_i16_sdwa v2, v203, sext(v2) dst_sel:DWORD dst_unused:UNUSED_PAD src0_sel:DWORD src1_sel:BYTE_0
	s_cmp_lt_i32 s0, 0
	s_movk_i32 s2, 0xb1
	v_and_b32_e32 v6, 32, v6
	v_bfe_i32 v12, v2, 0, 16
	s_cselect_b32 s2, s2, 0xb0
	v_add_lshl_u32 v2, v6, v12, 1
	s_mul_i32 s0, s0, s2
	v_lshl_add_u32 v130, v5, 12, v2
	v_lshl_add_u32 v132, v4, 12, v2
	v_bfe_i32 v2, v212, 27, 1
	s_add_i32 s0, s0, s1
	v_lshrrev_b32_e32 v2, 22, v2
	s_mul_hi_i32 s1, s0, 0x2e8ba2e9
	v_add_u32_e32 v2, v1, v2
	s_lshr_b32 s2, s1, 31
	s_ashr_i32 s1, s1, 6
	v_and_b32_e32 v2, 0xfffffc00, v2
	s_add_i32 s1, s1, s2
	v_sub_u32_e32 v1, v1, v2
	s_lshl_b32 s2, s1, 3
	s_mulk_i32 s1, 0x160
	v_lshrrev_b32_e32 v2, 4, v1
	v_ashrrev_i32_e32 v3, 31, v212
	s_sub_i32 s0, s0, s1
	v_bitop3_b32 v1, v2, v1, 32 bitop3:0x6c
	v_lshrrev_b32_e32 v3, 26, v3
	s_bfe_u32 s1, s0, 0x3001c
	v_ashrrev_i32_e32 v2, 31, v1
	v_add_u32_e32 v3, v212, v3
	s_add_i32 s1, s0, s1
	v_lshrrev_b32_e32 v2, 26, v2
	v_ashrrev_i32_e32 v14, 6, v3
	s_and_b32 s3, s1, 0xfff8
	v_add_u32_e32 v2, v1, v2
	v_lshlrev_b32_e32 v3, 3, v14
	s_sub_i32 s0, s0, s3
	v_ashrrev_i32_e32 v13, 6, v2
	v_and_b32_e32 v3, -16, v3
	s_sext_i32_i16 s0, s0
	v_add_u32_e32 v3, v13, v3
	s_add_i32 s26, s2, s0
	s_sext_i32_i16 s0, s1
	v_and_b32_e32 v4, 3, v13
	v_lshrrev_b32_e32 v5, 2, v3
	v_lshlrev_b32_e32 v6, 1, v3
	v_and_b32_e32 v2, 0xc0, v2
	s_lshr_b32 s6, s0, 3
	v_and_or_b32 v4, v3, s89, v4
	v_and_b32_e32 v5, 4, v5
	v_and_b32_e32 v6, 24, v6
	v_sub_u32_e32 v1, v1, v2
	s_ashr_i32 s27, s26, 31
	s_bfe_i64 s[2:3], s[6:7], 0x100000
	v_or3_b32 v4, v4, v5, v6
	v_lshlrev_b32_e32 v5, 5, v14
	v_ashrrev_i16_sdwa v1, v203, sext(v1) dst_sel:DWORD dst_unused:UNUSED_PAD src0_sel:DWORD src1_sel:BYTE_0
	s_lshl_b64 s[0:1], s[26:27], 20
	s_lshl_b64 s[2:3], s[2:3], 20
	v_and_b32_e32 v5, 32, v5
	v_bfe_i32 v15, v1, 0, 16
	s_add_u32 s30, s36, s2
	v_add_lshl_u32 v1, v5, v15, 1
	s_addc_u32 s31, s37, s3
	s_add_i32 s40, s38, 0
	v_lshl_add_u32 v134, v4, 12, v1
	s_add_i32 m0, s40, 0x10000
	v_lshl_add_u32 v136, v3, 12, v1
	global_load_lds_dwordx4 v134, s[30:31]
	s_add_i32 m0, s40, 0x12000
	s_add_u32 s2, s30, 0x80000
	global_load_lds_dwordx4 v130, s[30:31]
	s_addc_u32 s3, s31, 0
	s_add_i32 m0, s40, 0x14000
	v_mov_b32_e32 v135, v0
	global_load_lds_dwordx4 v134, s[2:3]
	s_add_i32 m0, s40, 0x16000
	s_add_u32 s28, s96, s0
	s_addc_u32 s29, s97, s1
	s_add_i32 s41, s40, 0x2000
	global_load_lds_dwordx4 v130, s[2:3]
	s_mov_b32 m0, s40
	s_add_u32 s0, s28, 0x80000
	global_load_lds_dwordx4 v136, s[28:29]
	s_mov_b32 m0, s41
	s_addc_u32 s1, s29, 0
	s_add_i32 s42, s40, 0x4000
	global_load_lds_dwordx4 v132, s[28:29]
	s_mov_b32 m0, s42
	s_add_i32 s43, s40, 0x6000
	global_load_lds_dwordx4 v136, s[0:1]
	s_mov_b32 m0, s43
	v_mov_b32_e32 v131, v0
	global_load_lds_dwordx4 v132, s[0:1]
	v_mov_b32_e32 v137, v0
	v_mov_b32_e32 v133, v0
	s_cmp_eq_u32 s11, 1
	v_lshl_add_u64 v[8:9], s[30:31], 0, v[134:135]
	v_lshl_add_u64 v[6:7], s[30:31], 0, v[130:131]
	v_lshl_add_u64 v[2:3], s[28:29], 0, v[136:137]
	s_cselect_b64 s[0:1], -1, 0
	s_cmp_lg_u32 s11, 1
	v_lshl_add_u64 v[4:5], s[28:29], 0, v[132:133]
	s_cbranch_scc1 .LBB0_405
	s_barrier

;     __device__ bool next(int i, Unit& u) const {
;         const long L = (long)i * G + c; if (L >= nwg) return false;
;         int wgid = (int)L; { const int q = nwg / NXCD, r = nwg % NXCD, xcd = wgid % NXCD, off = wgid / NXCD; wgid = (xcd < r ? xcd * (q + 1) : r * (q + 1) + (xcd - r) * q) + off; }
;         const int nig = WGM * nN, gid = wgid / nig, fm = gid * WGM, gsz = (nM - fm) < WGM ? (nM - fm) : WGM;
;         u.pm = __builtin_amdgcn_readfirstlane(fm + ((wgid % nig) % gsz)); u.pn = __builtin_amdgcn_readfirstlane((wgid % nig) / gsz); return true;
; template <class Epi>
; __device__ __forceinline__ void gemm_phase(LAS unsigned char* lds, const Gemm g, const StaticOrder& S, const Epi& E, const int tid) {
;     ...
;         const bool has_next = S.next(ui + 1, nxt);
;         const char* nA = has_next ? PG8_APTR(nxt) : cA; const char* nB = has_next ? PG8_BPTR(nxt) : cB;
.LBB0_408:
	s_add_i32 s49, s49, 1
	v_readlane_b32 s19, v255, 5
	s_cmpk_eq_i32 s19, 0x100
	s_cselect_b32 s19, 0xf0, s19
	s_mul_i32 s6, s49, s48
	s_mul_hi_u32 s7, s49, s19
	s_add_i32 s7, s7, s6
	s_mul_i32 s6, s49, s19
	s_add_u32 s22, s6, s94
	s_addc_u32 s23, s7, s39
	v_mov_b64_e32 v[2:3], 0x580
	v_cmp_lt_i64_e64 s[6:7], s[22:23], v[2:3]
	v_mov_b64_e32 v[2:3], 0x57f
	v_cmp_gt_i64_e32 vcc, s[22:23], v[2:3]
	s_cbranch_vccnz .LBB0_410
	s_ashr_i32 s18, s22, 31
	s_lshr_b32 s18, s18, 29
	s_add_i32 s18, s22, s18
	s_ashr_i32 s19, s18, 3
	s_and_b32 s18, s18, -8
	s_sub_i32 s18, s22, s18
	s_cmp_lt_i32 s18, 0
	s_movk_i32 s20, 0xb1
	s_cselect_b32 s20, s20, 0xb0
	s_mul_i32 s18, s18, s20
	s_add_i32 s18, s18, s19
	s_mul_hi_i32 s19, s18, 0x2e8ba2e9
	s_lshr_b32 s20, s19, 31
	s_ashr_i32 s19, s19, 6
	s_add_i32 s19, s19, s20
	s_lshl_b32 s20, s19, 3
	s_sub_i32 s21, 32, s20
	s_min_i32 s21, s21, 8
	s_abs_i32 s22, s21
	v_cvt_f32_u32_e32 v2, s22
	s_sub_i32 s24, 0, s22
	s_mulk_i32 s19, 0x160
	s_sub_i32 s19, s18, s19
	v_rcp_iflag_f32_e32 v2, v2
	s_abs_i32 s18, s19
	s_xor_b32 s23, s19, s21
	s_ashr_i32 s23, s23, 31
	v_mul_f32_e32 v2, 0x4f7ffffe, v2
	v_cvt_u32_f32_e32 v2, v2
	s_nop 0
	v_readfirstlane_b32 s25, v2
	s_mul_i32 s24, s24, s25
	s_mul_hi_u32 s24, s25, s24
	s_add_i32 s25, s25, s24
	s_mul_hi_u32 s24, s18, s25
	s_mul_i32 s25, s24, s22
	s_sub_i32 s18, s18, s25
	s_add_i32 s34, s24, 1
	s_sub_i32 s25, s18, s22
	s_cmp_ge_u32 s18, s22
	s_cselect_b32 s24, s34, s24
	s_cselect_b32 s18, s25, s18
	s_add_i32 s25, s24, 1
	s_cmp_ge_u32 s18, s22
	s_cselect_b32 s18, s25, s24
	s_xor_b32 s18, s18, s23
	s_sub_i32 s18, s18, s23
	s_mul_i32 s21, s18, s21
	s_sub_i32 s19, s19, s21
	s_add_i32 s20, s20, s19

; #define LAS __attribute__((address_space(3)))
; __device__ __forceinline__ void xpose_item(const float* src, int ld, bf16_t* dst, int K, int k0, LAS float* scr, int lane, const float* gk) {
;     if (src) {
; #pragma unroll 8
;         for (int i = 0; i < 32; ++i) { const int kk = 2 * i + (lane >> 5); scr[kk * 33 + (lane & 31)] = __builtin_nontemporal_load(src + (size_t)(k0 + kk) * ld + (lane & 31)); }
;     } else {
; #pragma unroll 8
;         for (int i = 0; i < 32; ++i) { const int kk = 2 * i + (lane >> 5); scr[kk * 33 + (lane & 31)] = 0.f; }
;     }
;     const int c = lane & 7;
;     f32x4 g0 = (f32x4){1.f, 1.f, 1.f, 1.f}, g1 = g0;
;     if (gk) { g0 = *(const f32x4*)(gk + k0 + 8 * c); g1 = *(const f32x4*)(gk + k0 + 8 * c + 4); }
;     asm volatile("s_waitcnt lgkmcnt(0)" ::: "memory");
; #pragma unroll
;     for (int j = 0; j < 4; ++j) { const int n = (lane >> 3) + 8 * j; const LAS float* s = scr + (8 * c) * 33 + n;
; __global__ void __launch_bounds__(512) mega(Args a_byval) {
;     ...
;                 it = xpose_all(a.in[15], nullptr, SSD_IN, 2048, SSD_IN, SSD_IN, 0, (bf16_t*)(ws + WS_WB_IN), it, NGW, scr, lane, norm_mix_g + D);
.LBB0_418:
	s_waitcnt vmcnt(0)
	s_barrier
	s_cmp_lg_u32 s76, 7
	s_cbranch_scc1 .Lxcd7_done
	v_readlane_b32 s59, v255, 5
	s_cmpk_lg_i32 s59, 0x100
	s_cbranch_scc1 .Lxcd7_done
	s_cmpk_lt_i32 s94, 0xf0
	s_cbranch_scc1 .Lxcd7_done
	s_cmpk_gt_i32 s94, 0xff
	s_cbranch_scc1 .Lxcd7_done
	s_sub_i32 s59, s94, 0xf0
	s_lshl_b32 s59, s59, 3
	s_add_i32 s59, s59, s95
	s_mul_i32 s64, s95, 0x2100
	v_and_b32_e32 v2, 31, v200
	v_lshrrev_b32_e32 v3, 5, v200
	v_lshlrev_b32_e32 v4, 2, v2
	v_mul_u32_u24_e32 v6, 0x84, v3
	v_add3_u32 v6, v6, v4, s64
	v_and_b32_e32 v7, 7, v200
	v_lshrrev_b32_e32 v8, 3, v200
	v_mul_u32_u24_e32 v9, 0x420, v7
	v_lshl_add_u32 v9, v8, 2, v9
	v_add_u32_e32 v9, s64, v9
	s_cmpk_ge_i32 s59, 0x2840
	s_cbranch_scc1 .Lxpwid7_end
	s_load_dwordx2 s[60:61], s[92:93], 0x78
	s_load_dwordx2 s[62:63], s[92:93], 0xe8
	s_load_dwordx2 s[64:65], s[92:93], 0x10
	v_mov_b32_e32 v5, 0xa100
	v_mul_u32_u24_e32 v5, v3, v5
	v_add_u32_e32 v5, v5, v4
	v_mov_b32_e32 v10, 0x1000
	v_mul_u32_u24_e32 v10, v8, v10
	v_lshl_add_u32 v12, v7, 4, v10
	v_add_u32_e32 v13, 0x8000, v12
	v_add_u32_e32 v14, 0x10000, v12
	v_add_u32_e32 v15, 0x18000, v12
	s_waitcnt lgkmcnt(0)
	s_add_u32 s62, s62, 0x8400000
	s_addc_u32 s63, s63, 0
	s_add_u32 s64, s64, 0x2000
	s_addc_u32 s65, s65, 0
	v_lshlrev_b32_e32 v16, 5, v7
	v_mov_b32_e32 v17, v0
	v_lshl_add_u64 v[16:17], s[64:65], 0, v[16:17]
	s_mul_hi_u32 s64, s59, 0xcb8728
	s_mul_i32 s65, s64, 0x142
	s_sub_i32 s65, s59, s65
	s_mul_i32 s66, s64, 0x284000
	s_lshl_b32 s67, s65, 7
	s_add_i32 s66, s66, s67
	s_add_u32 s66, s60, s66
	s_addc_u32 s67, s61, 0
	s_lshl_b32 s64, s64, 8
	s_mov_b32 s65, 0
	v_lshl_add_u64 v[18:19], s[64:65], 0, v[16:17]
	global_load_dwordx4 v[52:55], v[18:19], off
	global_load_dwordx4 v[56:59], v[18:19], off offset:16
	v_mov_b32_e32 v11, v5
	global_load_dword v20, v11, s[66:67] nt
	v_add_u32_e32 v11, 0x14200, v11
	global_load_dword v21, v11, s[66:67] nt
	v_add_u32_e32 v11, 0x14200, v11
	global_load_dword v22, v11, s[66:67] nt
	v_add_u32_e32 v11, 0x14200, v11
	global_load_dword v23, v11, s[66:67] nt
	v_add_u32_e32 v11, 0x14200, v11
	global_load_dword v24, v11, s[66:67] nt
	v_add_u32_e32 v11, 0x14200, v11
	global_load_dword v25, v11, s[66:67] nt
	v_add_u32_e32 v11, 0x14200, v11
	global_load_dword v26, v11, s[66:67] nt
	v_add_u32_e32 v11, 0x14200, v11
	global_load_dword v27, v11, s[66:67] nt
	v_add_u32_e32 v11, 0x14200, v11
	global_load_dword v28, v11, s[66:67] nt
	v_add_u32_e32 v11, 0x14200, v11
	global_load_dword v29, v11, s[66:67] nt
	v_add_u32_e32 v11, 0x14200, v11
	global_load_dword v30, v11, s[66:67] nt
	v_add_u32_e32 v11, 0x14200, v11
	global_load_dword v31, v11, s[66:67] nt
	v_add_u32_e32 v11, 0x14200, v11
	global_load_dword v32, v11, s[66:67] nt
	v_add_u32_e32 v11, 0x14200, v11
	global_load_dword v33, v11, s[66:67] nt
	v_add_u32_e32 v11, 0x14200, v11
	global_load_dword v34, v11, s[66:67] nt
	v_add_u32_e32 v11, 0x14200, v11
	global_load_dword v35, v11, s[66:67] nt
	v_add_u32_e32 v11, 0x14200, v11
	global_load_dword v36, v11, s[66:67] nt
	v_add_u32_e32 v11, 0x14200, v11
	global_load_dword v37, v11, s[66:67] nt
	v_add_u32_e32 v11, 0x14200, v11
	global_load_dword v38, v11, s[66:67] nt
	v_add_u32_e32 v11, 0x14200, v11
	global_load_dword v39, v11, s[66:67] nt
	v_add_u32_e32 v11, 0x14200, v11
	global_load_dword v40, v11, s[66:67] nt
	v_add_u32_e32 v11, 0x14200, v11
	global_load_dword v41, v11, s[66:67] nt
	v_add_u32_e32 v11, 0x14200, v11
	global_load_dword v42, v11, s[66:67] nt
	v_add_u32_e32 v11, 0x14200, v11
	global_load_dword v43, v11, s[66:67] nt
	v_add_u32_e32 v11, 0x14200, v11
	global_load_dword v44, v11, s[66:67] nt
	v_add_u32_e32 v11, 0x14200, v11
	global_load_dword v45, v11, s[66:67] nt
	v_add_u32_e32 v11, 0x14200, v11
	global_load_dword v46, v11, s[66:67] nt
	v_add_u32_e32 v11, 0x14200, v11
	global_load_dword v47, v11, s[66:67] nt
	v_add_u32_e32 v11, 0x14200, v11
	global_load_dword v48, v11, s[66:67] nt
	v_add_u32_e32 v11, 0x14200, v11
	global_load_dword v49, v11, s[66:67] nt
	v_add_u32_e32 v11, 0x14200, v11
	global_load_dword v50, v11, s[66:67] nt
	v_add_u32_e32 v11, 0x14200, v11
	global_load_dword v51, v11, s[66:67] nt
.Lxpwid7_loop:
	s_add_i32 s32, s59, 0x80
	s_cmpk_lt_i32 s32, 0x2840
	s_cbranch_scc0 .Lxpwid7_dumB
	s_mul_hi_u32 s64, s32, 0xcb8728
	s_mul_i32 s65, s64, 0x142
	s_sub_i32 s65, s32, s65
	s_mul_i32 s66, s64, 0x284000
	s_lshl_b32 s67, s65, 7
	s_add_i32 s66, s66, s67
	s_add_u32 s66, s60, s66
	s_addc_u32 s67, s61, 0
	s_lshl_b32 s64, s64, 8
	s_mov_b32 s65, 0
	v_lshl_add_u64 v[18:19], s[64:65], 0, v[16:17]
	global_load_dwordx4 v[160:163], v[18:19], off
	global_load_dwordx4 v[164:167], v[18:19], off offset:16
	v_mov_b32_e32 v11, v5
	global_load_dword v108, v11, s[66:67] nt
	v_add_u32_e32 v11, 0x14200, v11
	global_load_dword v109, v11, s[66:67] nt
	v_add_u32_e32 v11, 0x14200, v11
	global_load_dword v110, v11, s[66:67] nt
	v_add_u32_e32 v11, 0x14200, v11
	global_load_dword v111, v11, s[66:67] nt
	v_add_u32_e32 v11, 0x14200, v11
	global_load_dword v112, v11, s[66:67] nt
	v_add_u32_e32 v11, 0x14200, v11
	global_load_dword v113, v11, s[66:67] nt
	v_add_u32_e32 v11, 0x14200, v11
	global_load_dword v114, v11, s[66:67] nt
	v_add_u32_e32 v11, 0x14200, v11
	global_load_dword v115, v11, s[66:67] nt
	v_add_u32_e32 v11, 0x14200, v11
	global_load_dword v116, v11, s[66:67] nt
	v_add_u32_e32 v11, 0x14200, v11
	global_load_dword v117, v11, s[66:67] nt
	v_add_u32_e32 v11, 0x14200, v11
	global_load_dword v118, v11, s[66:67] nt
	v_add_u32_e32 v11, 0x14200, v11
	global_load_dword v119, v11, s[66:67] nt
	v_add_u32_e32 v11, 0x14200, v11
	global_load_dword v120, v11, s[66:67] nt
	v_add_u32_e32 v11, 0x14200, v11
	global_load_dword v121, v11, s[66:67] nt
	v_add_u32_e32 v11, 0x14200, v11
	global_load_dword v122, v11, s[66:67] nt
	v_add_u32_e32 v11, 0x14200, v11
	global_load_dword v123, v11, s[66:67] nt
	v_add_u32_e32 v11, 0x14200, v11
	global_load_dword v124, v11, s[66:67] nt
	v_add_u32_e32 v11, 0x14200, v11
	global_load_dword v125, v11, s[66:67] nt
	v_add_u32_e32 v11, 0x14200, v11
	global_load_dword v126, v11, s[66:67] nt
	v_add_u32_e32 v11, 0x14200, v11
	global_load_dword v127, v11, s[66:67] nt
	v_add_u32_e32 v11, 0x14200, v11
	global_load_dword v128, v11, s[66:67] nt
	v_add_u32_e32 v11, 0x14200, v11
	global_load_dword v129, v11, s[66:67] nt
	v_add_u32_e32 v11, 0x14200, v11
	global_load_dword v130, v11, s[66:67] nt
	v_add_u32_e32 v11, 0x14200, v11
	global_load_dword v131, v11, s[66:67] nt
	v_add_u32_e32 v11, 0x14200, v11
	global_load_dword v132, v11, s[66:67] nt
	v_add_u32_e32 v11, 0x14200, v11
	global_load_dword v133, v11, s[66:67] nt
	v_add_u32_e32 v11, 0x14200, v11
	global_load_dword v134, v11, s[66:67] nt
	v_add_u32_e32 v11, 0x14200, v11
	global_load_dword v135, v11, s[66:67] nt
	v_add_u32_e32 v11, 0x14200, v11
	global_load_dword v136, v11, s[66:67] nt
	v_add_u32_e32 v11, 0x14200, v11
	global_load_dword v137, v11, s[66:67] nt
	v_add_u32_e32 v11, 0x14200, v11
	global_load_dword v138, v11, s[66:67] nt
	v_add_u32_e32 v11, 0x14200, v11
	global_load_dword v139, v11, s[66:67] nt
	s_branch .Lxpwid7_procA

; #define LAS __attribute__((address_space(3)))
; __device__ __forceinline__ unsigned cvt_pk_bf16(float lo, float hi) { unsigned r; asm volatile("v_cvt_pk_bf16_f32 %0, %1, %2" : "=v"(r) : "v"(lo), "v"(hi)); return r; }
; __device__ __forceinline__ void xpose_item(const float* src, int ld, bf16_t* dst, int K, int k0, LAS float* scr, int lane, const float* gk) {
;     ...
;     const int c = lane & 7;
;     f32x4 g0 = (f32x4){1.f, 1.f, 1.f, 1.f}, g1 = g0;
;     if (gk) { g0 = *(const f32x4*)(gk + k0 + 8 * c); g1 = *(const f32x4*)(gk + k0 + 8 * c + 4); }
;     asm volatile("s_waitcnt lgkmcnt(0)" ::: "memory");
; #pragma unroll
;     for (int j = 0; j < 4; ++j) { const int n = (lane >> 3) + 8 * j; const LAS float* s = scr + (8 * c) * 33 + n;
;         u32x4 o; o.x = cvt_pk_bf16(s[0 * 33] * g0[0], s[1 * 33] * g0[1]); o.y = cvt_pk_bf16(s[2 * 33] * g0[2], s[3 * 33] * g0[3]); o.z = cvt_pk_bf16(s[4 * 33] * g1[0], s[5 * 33] * g1[1]); o.w = cvt_pk_bf16(s[6 * 33] * g1[2], s[7 * 33] * g1[3]);
;         *(u32x4*)(dst + (size_t)n * K + k0 + 8 * c) = o; }
.Lxpwid7_procA:
	s_mul_hi_u32 s64, s59, 0xcb8728
	s_mul_i32 s65, s64, 0x142
	s_sub_i32 s65, s59, s65
	s_mul_i32 s68, s65, 0x20000
	s_lshl_b32 s64, s64, 7
	s_add_i32 s68, s68, s64
	s_add_u32 s64, s62, s68
	s_addc_u32 s65, s63, 0
	s_waitcnt vmcnt(63)
	ds_write_b32 v6, v20 offset:0
	s_waitcnt vmcnt(62)
	ds_write_b32 v6, v21 offset:264
	s_waitcnt vmcnt(61)
	ds_write_b32 v6, v22 offset:528
	s_waitcnt vmcnt(60)
	ds_write_b32 v6, v23 offset:792
	s_waitcnt vmcnt(59)
	ds_write_b32 v6, v24 offset:1056
	s_waitcnt vmcnt(58)
	ds_write_b32 v6, v25 offset:1320
	s_waitcnt vmcnt(57)
	ds_write_b32 v6, v26 offset:1584
	s_waitcnt vmcnt(56)
	ds_write_b32 v6, v27 offset:1848
	s_waitcnt vmcnt(55)
	ds_write_b32 v6, v28 offset:2112
	s_waitcnt vmcnt(54)
	ds_write_b32 v6, v29 offset:2376
	s_waitcnt vmcnt(53)
	ds_write_b32 v6, v30 offset:2640
	s_waitcnt vmcnt(52)
	ds_write_b32 v6, v31 offset:2904
	s_waitcnt vmcnt(51)
	ds_write_b32 v6, v32 offset:3168
	s_waitcnt vmcnt(50)
	ds_write_b32 v6, v33 offset:3432
	s_waitcnt vmcnt(49)
	ds_write_b32 v6, v34 offset:3696
	s_waitcnt vmcnt(48)
	ds_write_b32 v6, v35 offset:3960
	s_waitcnt vmcnt(47)
	ds_write_b32 v6, v36 offset:4224
	s_waitcnt vmcnt(46)
	ds_write_b32 v6, v37 offset:4488
	s_waitcnt vmcnt(45)
	ds_write_b32 v6, v38 offset:4752
	s_waitcnt vmcnt(44)
	ds_write_b32 v6, v39 offset:5016
	s_waitcnt vmcnt(43)
	ds_write_b32 v6, v40 offset:5280
	s_waitcnt vmcnt(42)
	ds_write_b32 v6, v41 offset:5544
	s_waitcnt vmcnt(41)
	ds_write_b32 v6, v42 offset:5808
	s_waitcnt vmcnt(40)
	ds_write_b32 v6, v43 offset:6072
	s_waitcnt vmcnt(39)
	ds_write_b32 v6, v44 offset:6336
	s_waitcnt vmcnt(38)
	ds_write_b32 v6, v45 offset:6600
	s_waitcnt vmcnt(37)
	ds_write_b32 v6, v46 offset:6864
	s_waitcnt vmcnt(36)
	ds_write_b32 v6, v47 offset:7128
	s_waitcnt vmcnt(35)
	ds_write_b32 v6, v48 offset:7392
	s_waitcnt vmcnt(34)
	ds_write_b32 v6, v49 offset:7656
	s_waitcnt vmcnt(33)
	ds_write_b32 v6, v50 offset:7920
	s_waitcnt vmcnt(32)
	ds_write_b32 v6, v51 offset:8184
	s_waitcnt lgkmcnt(0)
	ds_read2_b32 v[60:61], v9 offset0:0 offset1:33
	ds_read2_b32 v[62:63], v9 offset0:66 offset1:99
	ds_read2_b32 v[64:65], v9 offset0:132 offset1:165
	ds_read2_b32 v[66:67], v9 offset0:198 offset1:231
	ds_read2_b32 v[68:69], v9 offset0:8 offset1:41
	ds_read2_b32 v[70:71], v9 offset0:74 offset1:107
	ds_read2_b32 v[72:73], v9 offset0:140 offset1:173
	ds_read2_b32 v[74:75], v9 offset0:206 offset1:239
	ds_read2_b32 v[76:77], v9 offset0:16 offset1:49
	ds_read2_b32 v[78:79], v9 offset0:82 offset1:115
	ds_read2_b32 v[80:81], v9 offset0:148 offset1:181
	ds_read2_b32 v[82:83], v9 offset0:214 offset1:247
	ds_read2_b32 v[84:85], v9 offset0:24 offset1:57
	ds_read2_b32 v[86:87], v9 offset0:90 offset1:123
	ds_read2_b32 v[88:89], v9 offset0:156 offset1:189
	ds_read2_b32 v[90:91], v9 offset0:222 offset1:255
	s_waitcnt lgkmcnt(12)
	v_mul_f32_e32 v60, v60, v52
	v_mul_f32_e32 v61, v61, v53
	v_mul_f32_e32 v62, v62, v54
	v_mul_f32_e32 v63, v63, v55
	v_mul_f32_e32 v64, v64, v56
	v_mul_f32_e32 v65, v65, v57
	v_mul_f32_e32 v66, v66, v58
	v_mul_f32_e32 v67, v67, v59
	v_cvt_pk_bf16_f32 v92, v60, v61
	v_cvt_pk_bf16_f32 v93, v62, v63
	v_cvt_pk_bf16_f32 v94, v64, v65
	v_cvt_pk_bf16_f32 v95, v66, v67
	global_store_dwordx4 v12, v[92:95], s[64:65]
	s_waitcnt lgkmcnt(8)
	v_mul_f32_e32 v68, v68, v52
	v_mul_f32_e32 v69, v69, v53
	v_mul_f32_e32 v70, v70, v54
	v_mul_f32_e32 v71, v71, v55
	v_mul_f32_e32 v72, v72, v56
	v_mul_f32_e32 v73, v73, v57
	v_mul_f32_e32 v74, v74, v58
	v_mul_f32_e32 v75, v75, v59
	v_cvt_pk_bf16_f32 v96, v68, v69
	v_cvt_pk_bf16_f32 v97, v70, v71
	v_cvt_pk_bf16_f32 v98, v72, v73
	v_cvt_pk_bf16_f32 v99, v74, v75
	global_store_dwordx4 v13, v[96:99], s[64:65]
	s_waitcnt lgkmcnt(4)
	v_mul_f32_e32 v76, v76, v52
	v_mul_f32_e32 v77, v77, v53
	v_mul_f32_e32 v78, v78, v54
	v_mul_f32_e32 v79, v79, v55
	v_mul_f32_e32 v80, v80, v56
	v_mul_f32_e32 v81, v81, v57
	v_mul_f32_e32 v82, v82, v58
	v_mul_f32_e32 v83, v83, v59
	v_cvt_pk_bf16_f32 v100, v76, v77
	v_cvt_pk_bf16_f32 v101, v78, v79
	v_cvt_pk_bf16_f32 v102, v80, v81
	v_cvt_pk_bf16_f32 v103, v82, v83
	global_store_dwordx4 v14, v[100:103], s[64:65]
	s_waitcnt lgkmcnt(0)
	v_mul_f32_e32 v84, v84, v52
	v_mul_f32_e32 v85, v85, v53
	v_mul_f32_e32 v86, v86, v54
	v_mul_f32_e32 v87, v87, v55
	v_mul_f32_e32 v88, v88, v56
	v_mul_f32_e32 v89, v89, v57
	v_mul_f32_e32 v90, v90, v58
	v_mul_f32_e32 v91, v91, v59
	v_cvt_pk_bf16_f32 v104, v84, v85
	v_cvt_pk_bf16_f32 v105, v86, v87
	v_cvt_pk_bf16_f32 v106, v88, v89
	v_cvt_pk_bf16_f32 v107, v90, v91
	global_store_dwordx4 v15, v[104:107], s[64:65]
	s_cmpk_lt_i32 s32, 0x2840
	s_cbranch_scc0 .Lxpwid7_fin
; __device__ __forceinline__ void xpose_item(const float* src, int ld, bf16_t* dst, int K, int k0, LAS float* scr, int lane, const float* gk) {
;     if (src) {
; #pragma unroll 8
;         for (int i = 0; i < 32; ++i) { const int kk = 2 * i + (lane >> 5); scr[kk * 33 + (lane & 31)] = __builtin_nontemporal_load(src + (size_t)(k0 + kk) * ld + (lane & 31)); }
	s_add_i32 s59, s32, 0x80
	s_cmpk_lt_i32 s59, 0x2840
	s_cbranch_scc0 .Lxpwid7_dumA
	s_mul_hi_u32 s64, s59, 0xcb8728
	s_mul_i32 s65, s64, 0x142
	s_sub_i32 s65, s59, s65
	s_mul_i32 s66, s64, 0x284000
	s_lshl_b32 s67, s65, 7
	s_add_i32 s66, s66, s67
	s_add_u32 s66, s60, s66
	s_addc_u32 s67, s61, 0
	s_lshl_b32 s64, s64, 8
	s_mov_b32 s65, 0
	v_lshl_add_u64 v[18:19], s[64:65], 0, v[16:17]
	global_load_dwordx4 v[52:55], v[18:19], off
	global_load_dwordx4 v[56:59], v[18:19], off offset:16
	v_mov_b32_e32 v11, v5
	global_load_dword v20, v11, s[66:67] nt
	v_add_u32_e32 v11, 0x14200, v11
	global_load_dword v21, v11, s[66:67] nt
	v_add_u32_e32 v11, 0x14200, v11
	global_load_dword v22, v11, s[66:67] nt
	v_add_u32_e32 v11, 0x14200, v11
	global_load_dword v23, v11, s[66:67] nt
	v_add_u32_e32 v11, 0x14200, v11
	global_load_dword v24, v11, s[66:67] nt
	v_add_u32_e32 v11, 0x14200, v11
	global_load_dword v25, v11, s[66:67] nt
	v_add_u32_e32 v11, 0x14200, v11
	global_load_dword v26, v11, s[66:67] nt
	v_add_u32_e32 v11, 0x14200, v11
	global_load_dword v27, v11, s[66:67] nt
	v_add_u32_e32 v11, 0x14200, v11
	global_load_dword v28, v11, s[66:67] nt
	v_add_u32_e32 v11, 0x14200, v11
	global_load_dword v29, v11, s[66:67] nt
	v_add_u32_e32 v11, 0x14200, v11
	global_load_dword v30, v11, s[66:67] nt
	v_add_u32_e32 v11, 0x14200, v11
	global_load_dword v31, v11, s[66:67] nt
	v_add_u32_e32 v11, 0x14200, v11
	global_load_dword v32, v11, s[66:67] nt
	v_add_u32_e32 v11, 0x14200, v11
	global_load_dword v33, v11, s[66:67] nt
	v_add_u32_e32 v11, 0x14200, v11
	global_load_dword v34, v11, s[66:67] nt
	v_add_u32_e32 v11, 0x14200, v11
	global_load_dword v35, v11, s[66:67] nt
	v_add_u32_e32 v11, 0x14200, v11
	global_load_dword v36, v11, s[66:67] nt
	v_add_u32_e32 v11, 0x14200, v11
	global_load_dword v37, v11, s[66:67] nt
	v_add_u32_e32 v11, 0x14200, v11
	global_load_dword v38, v11, s[66:67] nt
	v_add_u32_e32 v11, 0x14200, v11
	global_load_dword v39, v11, s[66:67] nt
	v_add_u32_e32 v11, 0x14200, v11
	global_load_dword v40, v11, s[66:67] nt
	v_add_u32_e32 v11, 0x14200, v11
	global_load_dword v41, v11, s[66:67] nt
	v_add_u32_e32 v11, 0x14200, v11
	global_load_dword v42, v11, s[66:67] nt
	v_add_u32_e32 v11, 0x14200, v11
	global_load_dword v43, v11, s[66:67] nt
	v_add_u32_e32 v11, 0x14200, v11
	global_load_dword v44, v11, s[66:67] nt
	v_add_u32_e32 v11, 0x14200, v11
	global_load_dword v45, v11, s[66:67] nt
	v_add_u32_e32 v11, 0x14200, v11
	global_load_dword v46, v11, s[66:67] nt
	v_add_u32_e32 v11, 0x14200, v11
	global_load_dword v47, v11, s[66:67] nt
	v_add_u32_e32 v11, 0x14200, v11
	global_load_dword v48, v11, s[66:67] nt
	v_add_u32_e32 v11, 0x14200, v11
	global_load_dword v49, v11, s[66:67] nt
	v_add_u32_e32 v11, 0x14200, v11
	global_load_dword v50, v11, s[66:67] nt
	v_add_u32_e32 v11, 0x14200, v11
	global_load_dword v51, v11, s[66:67] nt
	s_branch .Lxpwid7_procB

; #define LAS __attribute__((address_space(3)))
; __device__ __forceinline__ void xpose_item(const float* src, int ld, bf16_t* dst, int K, int k0, LAS float* scr, int lane, const float* gk) {
;     if (src) {
; #pragma unroll 8
;         for (int i = 0; i < 32; ++i) { const int kk = 2 * i + (lane >> 5); scr[kk * 33 + (lane & 31)] = __builtin_nontemporal_load(src + (size_t)(k0 + kk) * ld + (lane & 31)); }
;     } else {
; #pragma unroll 8
;         for (int i = 0; i < 32; ++i) { const int kk = 2 * i + (lane >> 5); scr[kk * 33 + (lane & 31)] = 0.f; }
;     }
;     const int c = lane & 7;
;     f32x4 g0 = (f32x4){1.f, 1.f, 1.f, 1.f}, g1 = g0;
;     if (gk) { g0 = *(const f32x4*)(gk + k0 + 8 * c); g1 = *(const f32x4*)(gk + k0 + 8 * c + 4); }
;     asm volatile("s_waitcnt lgkmcnt(0)" ::: "memory");
; #pragma unroll
;     for (int j = 0; j < 4; ++j) { const int n = (lane >> 3) + 8 * j; const LAS float* s = scr + (8 * c) * 33 + n;
; __global__ void __launch_bounds__(512) mega(Args a_byval) {
;     ...
;                 it = xpose_all(a.in[22], nullptr, 2048, 4096, 2048, 2048, 0, (bf16_t*)(ws + WS_WB_OUT), it, NGW, scr, lane);
.Lxpwid7_end:
	s_sub_i32 s59, s59, 0x2840
	s_movk_i32 s33, 0x84
.Lxcd7_done:
	s_cmp_lg_u32 s76, 7
	s_cbranch_scc1 .Lxct7_done
	v_readlane_b32 s59, v255, 5
	s_cmpk_lg_i32 s59, 0x100
	s_cbranch_scc1 .Lxct7_done
	s_cmpk_lt_i32 s94, 0xd0
	s_cbranch_scc1 .Lxct7_done
	s_cmpk_gt_i32 s94, 0xef
	s_cbranch_scc1 .Lxct7_done
	s_sub_i32 s59, s94, 0xd0
	s_lshl_b32 s59, s59, 3
	s_add_i32 s59, s59, s95
	s_mul_i32 s64, s95, 0x2100
	v_and_b32_e32 v2, 31, v200
	v_lshrrev_b32_e32 v3, 5, v200
	v_lshlrev_b32_e32 v4, 2, v2
	v_mul_u32_u24_e32 v6, 0x84, v3
	v_add3_u32 v6, v6, v4, s64
	v_and_b32_e32 v7, 7, v200
	v_lshrrev_b32_e32 v8, 3, v200
	v_mul_u32_u24_e32 v9, 0x420, v7
	v_lshl_add_u32 v9, v8, 2, v9
	v_add_u32_e32 v9, s64, v9
	s_cmpk_ge_i32 s59, 0x1000
	s_cbranch_scc1 .Lxpwot7_end
	s_load_dwordx2 s[60:61], s[92:93], 0xb0
	s_load_dwordx2 s[62:63], s[92:93], 0xe8
	v_mov_b32_e32 v5, 0x2000
	v_mul_u32_u24_e32 v5, v3, v5
	v_add_u32_e32 v5, v5, v4
	v_mov_b32_e32 v10, 0x2000
	v_mul_u32_u24_e32 v10, v8, v10
	v_lshl_add_u32 v12, v7, 4, v10
	v_add_u32_e32 v13, 0x10000, v12
	v_add_u32_e32 v14, 0x20000, v12
	v_add_u32_e32 v15, 0x30000, v12
	s_waitcnt lgkmcnt(0)
	s_add_u32 s62, s62, 0xad00000
	s_addc_u32 s63, s63, 0
	s_lshr_b32 s64, s59, 6
	s_and_b32 s65, s59, 63
	s_mul_i32 s66, s64, 0x80000
	s_lshl_b32 s67, s65, 7
	s_add_i32 s66, s66, s67
	s_add_u32 s66, s60, s66
	s_addc_u32 s67, s61, 0
	v_mov_b32_e32 v11, v5
	global_load_dword v20, v11, s[66:67] nt
	v_add_u32_e32 v11, 0x4000, v11
	global_load_dword v21, v11, s[66:67] nt
	v_add_u32_e32 v11, 0x4000, v11
	global_load_dword v22, v11, s[66:67] nt
	v_add_u32_e32 v11, 0x4000, v11
	global_load_dword v23, v11, s[66:67] nt
	v_add_u32_e32 v11, 0x4000, v11
	global_load_dword v24, v11, s[66:67] nt
	v_add_u32_e32 v11, 0x4000, v11
	global_load_dword v25, v11, s[66:67] nt
	v_add_u32_e32 v11, 0x4000, v11
	global_load_dword v26, v11, s[66:67] nt
	v_add_u32_e32 v11, 0x4000, v11
	global_load_dword v27, v11, s[66:67] nt
	v_add_u32_e32 v11, 0x4000, v11
	global_load_dword v28, v11, s[66:67] nt
	v_add_u32_e32 v11, 0x4000, v11
	global_load_dword v29, v11, s[66:67] nt
	v_add_u32_e32 v11, 0x4000, v11
	global_load_dword v30, v11, s[66:67] nt
	v_add_u32_e32 v11, 0x4000, v11
	global_load_dword v31, v11, s[66:67] nt
	v_add_u32_e32 v11, 0x4000, v11
	global_load_dword v32, v11, s[66:67] nt
	v_add_u32_e32 v11, 0x4000, v11
	global_load_dword v33, v11, s[66:67] nt
	v_add_u32_e32 v11, 0x4000, v11
	global_load_dword v34, v11, s[66:67] nt
	v_add_u32_e32 v11, 0x4000, v11
	global_load_dword v35, v11, s[66:67] nt
	v_add_u32_e32 v11, 0x4000, v11
	global_load_dword v36, v11, s[66:67] nt
	v_add_u32_e32 v11, 0x4000, v11
	global_load_dword v37, v11, s[66:67] nt
	v_add_u32_e32 v11, 0x4000, v11
	global_load_dword v38, v11, s[66:67] nt
	v_add_u32_e32 v11, 0x4000, v11
	global_load_dword v39, v11, s[66:67] nt
	v_add_u32_e32 v11, 0x4000, v11
	global_load_dword v40, v11, s[66:67] nt
	v_add_u32_e32 v11, 0x4000, v11
	global_load_dword v41, v11, s[66:67] nt
	v_add_u32_e32 v11, 0x4000, v11
	global_load_dword v42, v11, s[66:67] nt
	v_add_u32_e32 v11, 0x4000, v11
	global_load_dword v43, v11, s[66:67] nt
	v_add_u32_e32 v11, 0x4000, v11
	global_load_dword v44, v11, s[66:67] nt
	v_add_u32_e32 v11, 0x4000, v11
	global_load_dword v45, v11, s[66:67] nt
	v_add_u32_e32 v11, 0x4000, v11
	global_load_dword v46, v11, s[66:67] nt
	v_add_u32_e32 v11, 0x4000, v11
	global_load_dword v47, v11, s[66:67] nt
	v_add_u32_e32 v11, 0x4000, v11
	global_load_dword v48, v11, s[66:67] nt
	v_add_u32_e32 v11, 0x4000, v11
	global_load_dword v49, v11, s[66:67] nt
	v_add_u32_e32 v11, 0x4000, v11
	global_load_dword v50, v11, s[66:67] nt
	v_add_u32_e32 v11, 0x4000, v11
	global_load_dword v51, v11, s[66:67] nt
.Lxpwot7_loop:
	s_add_i32 s32, s59, 0x100
	s_cmpk_lt_i32 s32, 0x1000
	s_cbranch_scc0 .Lxpwot7_dumB
	s_lshr_b32 s64, s32, 6
	s_and_b32 s65, s32, 63
	s_mul_i32 s66, s64, 0x80000
	s_lshl_b32 s67, s65, 7
	s_add_i32 s66, s66, s67
	s_add_u32 s66, s60, s66
	s_addc_u32 s67, s61, 0
	v_mov_b32_e32 v11, v5
	global_load_dword v108, v11, s[66:67] nt
	v_add_u32_e32 v11, 0x4000, v11
	global_load_dword v109, v11, s[66:67] nt
	v_add_u32_e32 v11, 0x4000, v11
	global_load_dword v110, v11, s[66:67] nt
	v_add_u32_e32 v11, 0x4000, v11
	global_load_dword v111, v11, s[66:67] nt
	v_add_u32_e32 v11, 0x4000, v11
	global_load_dword v112, v11, s[66:67] nt
	v_add_u32_e32 v11, 0x4000, v11
	global_load_dword v113, v11, s[66:67] nt
	v_add_u32_e32 v11, 0x4000, v11
	global_load_dword v114, v11, s[66:67] nt
	v_add_u32_e32 v11, 0x4000, v11
	global_load_dword v115, v11, s[66:67] nt
	v_add_u32_e32 v11, 0x4000, v11
	global_load_dword v116, v11, s[66:67] nt
	v_add_u32_e32 v11, 0x4000, v11
	global_load_dword v117, v11, s[66:67] nt
	v_add_u32_e32 v11, 0x4000, v11
	global_load_dword v118, v11, s[66:67] nt
	v_add_u32_e32 v11, 0x4000, v11
	global_load_dword v119, v11, s[66:67] nt
	v_add_u32_e32 v11, 0x4000, v11
	global_load_dword v120, v11, s[66:67] nt
	v_add_u32_e32 v11, 0x4000, v11
	global_load_dword v121, v11, s[66:67] nt
	v_add_u32_e32 v11, 0x4000, v11
	global_load_dword v122, v11, s[66:67] nt
	v_add_u32_e32 v11, 0x4000, v11
	global_load_dword v123, v11, s[66:67] nt
	v_add_u32_e32 v11, 0x4000, v11
	global_load_dword v124, v11, s[66:67] nt
	v_add_u32_e32 v11, 0x4000, v11
	global_load_dword v125, v11, s[66:67] nt
	v_add_u32_e32 v11, 0x4000, v11
	global_load_dword v126, v11, s[66:67] nt
	v_add_u32_e32 v11, 0x4000, v11
	global_load_dword v127, v11, s[66:67] nt
	v_add_u32_e32 v11, 0x4000, v11
	global_load_dword v128, v11, s[66:67] nt
	v_add_u32_e32 v11, 0x4000, v11
	global_load_dword v129, v11, s[66:67] nt
	v_add_u32_e32 v11, 0x4000, v11
	global_load_dword v130, v11, s[66:67] nt
	v_add_u32_e32 v11, 0x4000, v11
	global_load_dword v131, v11, s[66:67] nt
	v_add_u32_e32 v11, 0x4000, v11
	global_load_dword v132, v11, s[66:67] nt
	v_add_u32_e32 v11, 0x4000, v11
	global_load_dword v133, v11, s[66:67] nt
	v_add_u32_e32 v11, 0x4000, v11
	global_load_dword v134, v11, s[66:67] nt
	v_add_u32_e32 v11, 0x4000, v11
	global_load_dword v135, v11, s[66:67] nt
	v_add_u32_e32 v11, 0x4000, v11
	global_load_dword v136, v11, s[66:67] nt
	v_add_u32_e32 v11, 0x4000, v11
	global_load_dword v137, v11, s[66:67] nt
	v_add_u32_e32 v11, 0x4000, v11
	global_load_dword v138, v11, s[66:67] nt
	v_add_u32_e32 v11, 0x4000, v11
	global_load_dword v139, v11, s[66:67] nt
	s_branch .Lxpwot7_procA

; #define LAS __attribute__((address_space(3)))
; __device__ __forceinline__ unsigned cvt_pk_bf16(float lo, float hi) { unsigned r; asm volatile("v_cvt_pk_bf16_f32 %0, %1, %2" : "=v"(r) : "v"(lo), "v"(hi)); return r; }
; __device__ __forceinline__ void xpose_item(const float* src, int ld, bf16_t* dst, int K, int k0, LAS float* scr, int lane, const float* gk) {
;     ...
;         for (int i = 0; i < 32; ++i) { const int kk = 2 * i + (lane >> 5); scr[kk * 33 + (lane & 31)] = __builtin_nontemporal_load(src + (size_t)(k0 + kk) * ld + (lane & 31)); }
;     } else {
; #pragma unroll 8
;         for (int i = 0; i < 32; ++i) { const int kk = 2 * i + (lane >> 5); scr[kk * 33 + (lane & 31)] = 0.f; }
;     }
;     const int c = lane & 7;
;     f32x4 g0 = (f32x4){1.f, 1.f, 1.f, 1.f}, g1 = g0;
;     if (gk) { g0 = *(const f32x4*)(gk + k0 + 8 * c); g1 = *(const f32x4*)(gk + k0 + 8 * c + 4); }
;     asm volatile("s_waitcnt lgkmcnt(0)" ::: "memory");
; #pragma unroll
;     for (int j = 0; j < 4; ++j) { const int n = (lane >> 3) + 8 * j; const LAS float* s = scr + (8 * c) * 33 + n;
;         u32x4 o; o.x = cvt_pk_bf16(s[0 * 33] * g0[0], s[1 * 33] * g0[1]); o.y = cvt_pk_bf16(s[2 * 33] * g0[2], s[3 * 33] * g0[3]); o.z = cvt_pk_bf16(s[4 * 33] * g1[0], s[5 * 33] * g1[1]); o.w = cvt_pk_bf16(s[6 * 33] * g1[2], s[7 * 33] * g1[3]);
;         *(u32x4*)(dst + (size_t)n * K + k0 + 8 * c) = o; }
.Lxpwot7_procA:
	s_lshr_b32 s64, s59, 6
	s_and_b32 s65, s59, 63
	s_mul_i32 s68, s65, 0x40000
	s_lshl_b32 s64, s64, 7
	s_add_i32 s68, s68, s64
	s_add_u32 s64, s62, s68
	s_addc_u32 s65, s63, 0
	s_waitcnt vmcnt(63)
	ds_write_b32 v6, v20 offset:0
	s_waitcnt vmcnt(62)
	ds_write_b32 v6, v21 offset:264
	s_waitcnt vmcnt(61)
	ds_write_b32 v6, v22 offset:528
	s_waitcnt vmcnt(60)
	ds_write_b32 v6, v23 offset:792
	s_waitcnt vmcnt(59)
	ds_write_b32 v6, v24 offset:1056
	s_waitcnt vmcnt(58)
	ds_write_b32 v6, v25 offset:1320
	s_waitcnt vmcnt(57)
	ds_write_b32 v6, v26 offset:1584
	s_waitcnt vmcnt(56)
	ds_write_b32 v6, v27 offset:1848
	s_waitcnt vmcnt(55)
	ds_write_b32 v6, v28 offset:2112
	s_waitcnt vmcnt(54)
	ds_write_b32 v6, v29 offset:2376
	s_waitcnt vmcnt(53)
	ds_write_b32 v6, v30 offset:2640
	s_waitcnt vmcnt(52)
	ds_write_b32 v6, v31 offset:2904
	s_waitcnt vmcnt(51)
	ds_write_b32 v6, v32 offset:3168
	s_waitcnt vmcnt(50)
	ds_write_b32 v6, v33 offset:3432
	s_waitcnt vmcnt(49)
	ds_write_b32 v6, v34 offset:3696
	s_waitcnt vmcnt(48)
	ds_write_b32 v6, v35 offset:3960
	s_waitcnt vmcnt(47)
	ds_write_b32 v6, v36 offset:4224
	s_waitcnt vmcnt(46)
	ds_write_b32 v6, v37 offset:4488
	s_waitcnt vmcnt(45)
	ds_write_b32 v6, v38 offset:4752
	s_waitcnt vmcnt(44)
	ds_write_b32 v6, v39 offset:5016
	s_waitcnt vmcnt(43)
	ds_write_b32 v6, v40 offset:5280
	s_waitcnt vmcnt(42)
	ds_write_b32 v6, v41 offset:5544
	s_waitcnt vmcnt(41)
	ds_write_b32 v6, v42 offset:5808
	s_waitcnt vmcnt(40)
	ds_write_b32 v6, v43 offset:6072
	s_waitcnt vmcnt(39)
	ds_write_b32 v6, v44 offset:6336
	s_waitcnt vmcnt(38)
	ds_write_b32 v6, v45 offset:6600
	s_waitcnt vmcnt(37)
	ds_write_b32 v6, v46 offset:6864
	s_waitcnt vmcnt(36)
	ds_write_b32 v6, v47 offset:7128
	s_waitcnt vmcnt(35)
	ds_write_b32 v6, v48 offset:7392
	s_waitcnt vmcnt(34)
	ds_write_b32 v6, v49 offset:7656
	s_waitcnt vmcnt(33)
	ds_write_b32 v6, v50 offset:7920
	s_waitcnt vmcnt(32)
	ds_write_b32 v6, v51 offset:8184
	s_waitcnt lgkmcnt(0)
	ds_read2_b32 v[60:61], v9 offset0:0 offset1:33
	ds_read2_b32 v[62:63], v9 offset0:66 offset1:99
	ds_read2_b32 v[64:65], v9 offset0:132 offset1:165
	ds_read2_b32 v[66:67], v9 offset0:198 offset1:231
	ds_read2_b32 v[68:69], v9 offset0:8 offset1:41
	ds_read2_b32 v[70:71], v9 offset0:74 offset1:107
	ds_read2_b32 v[72:73], v9 offset0:140 offset1:173
	ds_read2_b32 v[74:75], v9 offset0:206 offset1:239
	ds_read2_b32 v[76:77], v9 offset0:16 offset1:49
	ds_read2_b32 v[78:79], v9 offset0:82 offset1:115
	ds_read2_b32 v[80:81], v9 offset0:148 offset1:181
	ds_read2_b32 v[82:83], v9 offset0:214 offset1:247
	ds_read2_b32 v[84:85], v9 offset0:24 offset1:57
	ds_read2_b32 v[86:87], v9 offset0:90 offset1:123
	ds_read2_b32 v[88:89], v9 offset0:156 offset1:189
	ds_read2_b32 v[90:91], v9 offset0:222 offset1:255
	s_waitcnt lgkmcnt(12)
	v_cvt_pk_bf16_f32 v92, v60, v61
	v_cvt_pk_bf16_f32 v93, v62, v63
	v_cvt_pk_bf16_f32 v94, v64, v65
	v_cvt_pk_bf16_f32 v95, v66, v67
	global_store_dwordx4 v12, v[92:95], s[64:65]
	s_waitcnt lgkmcnt(8)
	v_cvt_pk_bf16_f32 v96, v68, v69
	v_cvt_pk_bf16_f32 v97, v70, v71
	v_cvt_pk_bf16_f32 v98, v72, v73
	v_cvt_pk_bf16_f32 v99, v74, v75
	global_store_dwordx4 v13, v[96:99], s[64:65]
	s_waitcnt lgkmcnt(4)
	v_cvt_pk_bf16_f32 v100, v76, v77
	v_cvt_pk_bf16_f32 v101, v78, v79
	v_cvt_pk_bf16_f32 v102, v80, v81
	v_cvt_pk_bf16_f32 v103, v82, v83
	global_store_dwordx4 v14, v[100:103], s[64:65]
	s_waitcnt lgkmcnt(0)
	v_cvt_pk_bf16_f32 v104, v84, v85
	v_cvt_pk_bf16_f32 v105, v86, v87
	v_cvt_pk_bf16_f32 v106, v88, v89
	v_cvt_pk_bf16_f32 v107, v90, v91
	global_store_dwordx4 v15, v[104:107], s[64:65]
	s_cmpk_lt_i32 s32, 0x1000
	s_cbranch_scc0 .Lxpwot7_fin
	s_add_i32 s59, s32, 0x100
	s_cmpk_lt_i32 s59, 0x1000
	s_cbranch_scc0 .Lxpwot7_dumA
	s_lshr_b32 s64, s59, 6
	s_and_b32 s65, s59, 63
	s_mul_i32 s66, s64, 0x80000
	s_lshl_b32 s67, s65, 7
	s_add_i32 s66, s66, s67
	s_add_u32 s66, s60, s66
	s_addc_u32 s67, s61, 0
	v_mov_b32_e32 v11, v5
	global_load_dword v20, v11, s[66:67] nt
	v_add_u32_e32 v11, 0x4000, v11
	global_load_dword v21, v11, s[66:67] nt
	v_add_u32_e32 v11, 0x4000, v11
	global_load_dword v22, v11, s[66:67] nt
	v_add_u32_e32 v11, 0x4000, v11
	global_load_dword v23, v11, s[66:67] nt
	v_add_u32_e32 v11, 0x4000, v11
	global_load_dword v24, v11, s[66:67] nt
	v_add_u32_e32 v11, 0x4000, v11
	global_load_dword v25, v11, s[66:67] nt
	v_add_u32_e32 v11, 0x4000, v11
	global_load_dword v26, v11, s[66:67] nt
	v_add_u32_e32 v11, 0x4000, v11
	global_load_dword v27, v11, s[66:67] nt
	v_add_u32_e32 v11, 0x4000, v11
	global_load_dword v28, v11, s[66:67] nt
	v_add_u32_e32 v11, 0x4000, v11
	global_load_dword v29, v11, s[66:67] nt
	v_add_u32_e32 v11, 0x4000, v11
	global_load_dword v30, v11, s[66:67] nt
	v_add_u32_e32 v11, 0x4000, v11
	global_load_dword v31, v11, s[66:67] nt
	v_add_u32_e32 v11, 0x4000, v11
	global_load_dword v32, v11, s[66:67] nt
	v_add_u32_e32 v11, 0x4000, v11
	global_load_dword v33, v11, s[66:67] nt
	v_add_u32_e32 v11, 0x4000, v11
	global_load_dword v34, v11, s[66:67] nt
	v_add_u32_e32 v11, 0x4000, v11
	global_load_dword v35, v11, s[66:67] nt
	v_add_u32_e32 v11, 0x4000, v11
	global_load_dword v36, v11, s[66:67] nt
	v_add_u32_e32 v11, 0x4000, v11
	global_load_dword v37, v11, s[66:67] nt
	v_add_u32_e32 v11, 0x4000, v11
	global_load_dword v38, v11, s[66:67] nt
	v_add_u32_e32 v11, 0x4000, v11
	global_load_dword v39, v11, s[66:67] nt
	v_add_u32_e32 v11, 0x4000, v11
	global_load_dword v40, v11, s[66:67] nt
	v_add_u32_e32 v11, 0x4000, v11
	global_load_dword v41, v11, s[66:67] nt
	v_add_u32_e32 v11, 0x4000, v11
	global_load_dword v42, v11, s[66:67] nt
	v_add_u32_e32 v11, 0x4000, v11
	global_load_dword v43, v11, s[66:67] nt
	v_add_u32_e32 v11, 0x4000, v11
	global_load_dword v44, v11, s[66:67] nt
	v_add_u32_e32 v11, 0x4000, v11
	global_load_dword v45, v11, s[66:67] nt
	v_add_u32_e32 v11, 0x4000, v11
	global_load_dword v46, v11, s[66:67] nt
	v_add_u32_e32 v11, 0x4000, v11
	global_load_dword v47, v11, s[66:67] nt
	v_add_u32_e32 v11, 0x4000, v11
	global_load_dword v48, v11, s[66:67] nt
	v_add_u32_e32 v11, 0x4000, v11
	global_load_dword v49, v11, s[66:67] nt
	v_add_u32_e32 v11, 0x4000, v11
	global_load_dword v50, v11, s[66:67] nt
	v_add_u32_e32 v11, 0x4000, v11
	global_load_dword v51, v11, s[66:67] nt
	s_branch .Lxpwot7_procB

; #define LAS __attribute__((address_space(3)))
; __device__ __forceinline__ void xpose_item(const float* src, int ld, bf16_t* dst, int K, int k0, LAS float* scr, int lane, const float* gk) {
;     if (src) {
; #pragma unroll 8
;         for (int i = 0; i < 32; ++i) { const int kk = 2 * i + (lane >> 5); scr[kk * 33 + (lane & 31)] = __builtin_nontemporal_load(src + (size_t)(k0 + kk) * ld + (lane & 31)); }
;     } else {
; #pragma unroll 8
;         for (int i = 0; i < 32; ++i) { const int kk = 2 * i + (lane >> 5); scr[kk * 33 + (lane & 31)] = 0.f; }
;     }
;     const int c = lane & 7;
;     f32x4 g0 = (f32x4){1.f, 1.f, 1.f, 1.f}, g1 = g0;
;     if (gk) { g0 = *(const f32x4*)(gk + k0 + 8 * c); g1 = *(const f32x4*)(gk + k0 + 8 * c + 4); }
;     asm volatile("s_waitcnt lgkmcnt(0)" ::: "memory");
; #pragma unroll
;     for (int j = 0; j < 4; ++j) { const int n = (lane >> 3) + 8 * j; const LAS float* s = scr + (8 * c) * 33 + n;
; __global__ void __launch_bounds__(512) mega(Args a_byval) {
;     ...
;             it = xpose_all(a.in[25] + (size_t)lyr * D * DFF, nullptr, 2048, DFF, 2048, 2048, 0, (bf16_t*)(ws + (lyr ? WS_W_D : WS_W_D0)), it, NGW, scr, lane);
.Lxpwot7_end:
	s_sub_i32 s59, s59, 0x1000
	s_movk_i32 s33, 0x84
.Lxct7_done:
	s_cmp_lg_u32 s76, 19
	s_cbranch_scc1 .Lxcd19_done
	v_readlane_b32 s59, v255, 5
	s_cmpk_lg_i32 s59, 0x100
	s_cbranch_scc1 .Lxcd19_done
	s_cmpk_lt_i32 s94, 0xf0
	s_cbranch_scc1 .Lxcd19_done
	s_cmpk_gt_i32 s94, 0xff
	s_cbranch_scc1 .Lxcd19_done
	s_sub_i32 s59, s94, 0xf0
	s_lshl_b32 s59, s59, 3
	s_add_i32 s59, s59, s95
	s_mul_i32 s64, s95, 0x2100
	v_and_b32_e32 v2, 31, v200
	v_lshrrev_b32_e32 v3, 5, v200
	v_lshlrev_b32_e32 v4, 2, v2
	v_mul_u32_u24_e32 v6, 0x84, v3
	v_add3_u32 v6, v6, v4, s64
	v_and_b32_e32 v7, 7, v200
	v_lshrrev_b32_e32 v8, 3, v200
	v_mul_u32_u24_e32 v9, 0x420, v7
	v_lshl_add_u32 v9, v8, 2, v9
	v_add_u32_e32 v9, s64, v9
	s_cmpk_ge_i32 s59, 0x1600
	s_cbranch_scc1 .Lxpfdd19_end
	s_load_dwordx2 s[60:61], s[92:93], 0xc8
	s_load_dwordx2 s[62:63], s[92:93], 0xe8
	v_mov_b32_e32 v5, 0x2000
	v_mul_u32_u24_e32 v5, v3, v5
	v_add_u32_e32 v5, v5, v4
	v_mov_b32_e32 v10, 0x2c00
	v_mul_u32_u24_e32 v10, v8, v10
	v_lshl_add_u32 v12, v7, 4, v10
	v_add_u32_e32 v13, 0x16000, v12
	v_add_u32_e32 v14, 0x2c000, v12
	v_add_u32_e32 v15, 0x42000, v12
	s_waitcnt lgkmcnt(0)
	s_add_u32 s60, s60, 0x2c00000
	s_addc_u32 s61, s61, 0
	s_add_u32 s62, s62, 0x6500000
	s_addc_u32 s63, s63, 0
	s_lshr_b32 s64, s59, 6
	s_and_b32 s65, s59, 63
	s_mul_i32 s66, s64, 0x80000
	s_lshl_b32 s67, s65, 7
	s_add_i32 s66, s66, s67
	s_add_u32 s66, s60, s66
	s_addc_u32 s67, s61, 0
	v_mov_b32_e32 v11, v5
	global_load_dword v20, v11, s[66:67] nt
	v_add_u32_e32 v11, 0x4000, v11
	global_load_dword v21, v11, s[66:67] nt
	v_add_u32_e32 v11, 0x4000, v11
	global_load_dword v22, v11, s[66:67] nt
	v_add_u32_e32 v11, 0x4000, v11
	global_load_dword v23, v11, s[66:67] nt
	v_add_u32_e32 v11, 0x4000, v11
	global_load_dword v24, v11, s[66:67] nt
	v_add_u32_e32 v11, 0x4000, v11
	global_load_dword v25, v11, s[66:67] nt
	v_add_u32_e32 v11, 0x4000, v11
	global_load_dword v26, v11, s[66:67] nt
	v_add_u32_e32 v11, 0x4000, v11
	global_load_dword v27, v11, s[66:67] nt
	v_add_u32_e32 v11, 0x4000, v11
	global_load_dword v28, v11, s[66:67] nt
	v_add_u32_e32 v11, 0x4000, v11
	global_load_dword v29, v11, s[66:67] nt
	v_add_u32_e32 v11, 0x4000, v11
	global_load_dword v30, v11, s[66:67] nt
	v_add_u32_e32 v11, 0x4000, v11
	global_load_dword v31, v11, s[66:67] nt
	v_add_u32_e32 v11, 0x4000, v11
	global_load_dword v32, v11, s[66:67] nt
	v_add_u32_e32 v11, 0x4000, v11
	global_load_dword v33, v11, s[66:67] nt
	v_add_u32_e32 v11, 0x4000, v11
	global_load_dword v34, v11, s[66:67] nt
	v_add_u32_e32 v11, 0x4000, v11
	global_load_dword v35, v11, s[66:67] nt
	v_add_u32_e32 v11, 0x4000, v11
	global_load_dword v36, v11, s[66:67] nt
	v_add_u32_e32 v11, 0x4000, v11
	global_load_dword v37, v11, s[66:67] nt
	v_add_u32_e32 v11, 0x4000, v11
	global_load_dword v38, v11, s[66:67] nt
	v_add_u32_e32 v11, 0x4000, v11
	global_load_dword v39, v11, s[66:67] nt
	v_add_u32_e32 v11, 0x4000, v11
	global_load_dword v40, v11, s[66:67] nt
	v_add_u32_e32 v11, 0x4000, v11
	global_load_dword v41, v11, s[66:67] nt
	v_add_u32_e32 v11, 0x4000, v11
	global_load_dword v42, v11, s[66:67] nt
	v_add_u32_e32 v11, 0x4000, v11
	global_load_dword v43, v11, s[66:67] nt
	v_add_u32_e32 v11, 0x4000, v11
	global_load_dword v44, v11, s[66:67] nt
	v_add_u32_e32 v11, 0x4000, v11
	global_load_dword v45, v11, s[66:67] nt
	v_add_u32_e32 v11, 0x4000, v11
	global_load_dword v46, v11, s[66:67] nt
	v_add_u32_e32 v11, 0x4000, v11
	global_load_dword v47, v11, s[66:67] nt
	v_add_u32_e32 v11, 0x4000, v11
	global_load_dword v48, v11, s[66:67] nt
	v_add_u32_e32 v11, 0x4000, v11
	global_load_dword v49, v11, s[66:67] nt
	v_add_u32_e32 v11, 0x4000, v11
	global_load_dword v50, v11, s[66:67] nt
	v_add_u32_e32 v11, 0x4000, v11
	global_load_dword v51, v11, s[66:67] nt
.Lxpfdd19_loop:
	s_add_i32 s32, s59, 0x80
	s_cmpk_lt_i32 s32, 0x1600
	s_cbranch_scc0 .Lxpfdd19_dumB
	s_lshr_b32 s64, s32, 6
	s_and_b32 s65, s32, 63
	s_mul_i32 s66, s64, 0x80000
	s_lshl_b32 s67, s65, 7
	s_add_i32 s66, s66, s67
	s_add_u32 s66, s60, s66
	s_addc_u32 s67, s61, 0
	v_mov_b32_e32 v11, v5
	global_load_dword v108, v11, s[66:67] nt
	v_add_u32_e32 v11, 0x4000, v11
	global_load_dword v109, v11, s[66:67] nt
	v_add_u32_e32 v11, 0x4000, v11
	global_load_dword v110, v11, s[66:67] nt
	v_add_u32_e32 v11, 0x4000, v11
	global_load_dword v111, v11, s[66:67] nt
	v_add_u32_e32 v11, 0x4000, v11
	global_load_dword v112, v11, s[66:67] nt
	v_add_u32_e32 v11, 0x4000, v11
	global_load_dword v113, v11, s[66:67] nt
	v_add_u32_e32 v11, 0x4000, v11
	global_load_dword v114, v11, s[66:67] nt
	v_add_u32_e32 v11, 0x4000, v11
	global_load_dword v115, v11, s[66:67] nt
	v_add_u32_e32 v11, 0x4000, v11
	global_load_dword v116, v11, s[66:67] nt
	v_add_u32_e32 v11, 0x4000, v11
	global_load_dword v117, v11, s[66:67] nt
	v_add_u32_e32 v11, 0x4000, v11
	global_load_dword v118, v11, s[66:67] nt
	v_add_u32_e32 v11, 0x4000, v11
	global_load_dword v119, v11, s[66:67] nt
	v_add_u32_e32 v11, 0x4000, v11
	global_load_dword v120, v11, s[66:67] nt
	v_add_u32_e32 v11, 0x4000, v11
	global_load_dword v121, v11, s[66:67] nt
	v_add_u32_e32 v11, 0x4000, v11
	global_load_dword v122, v11, s[66:67] nt
	v_add_u32_e32 v11, 0x4000, v11
	global_load_dword v123, v11, s[66:67] nt
	v_add_u32_e32 v11, 0x4000, v11
	global_load_dword v124, v11, s[66:67] nt
	v_add_u32_e32 v11, 0x4000, v11
	global_load_dword v125, v11, s[66:67] nt
	v_add_u32_e32 v11, 0x4000, v11
	global_load_dword v126, v11, s[66:67] nt
	v_add_u32_e32 v11, 0x4000, v11
	global_load_dword v127, v11, s[66:67] nt
	v_add_u32_e32 v11, 0x4000, v11
	global_load_dword v128, v11, s[66:67] nt
	v_add_u32_e32 v11, 0x4000, v11
	global_load_dword v129, v11, s[66:67] nt
	v_add_u32_e32 v11, 0x4000, v11
	global_load_dword v130, v11, s[66:67] nt
	v_add_u32_e32 v11, 0x4000, v11
	global_load_dword v131, v11, s[66:67] nt
	v_add_u32_e32 v11, 0x4000, v11
	global_load_dword v132, v11, s[66:67] nt
	v_add_u32_e32 v11, 0x4000, v11
	global_load_dword v133, v11, s[66:67] nt
	v_add_u32_e32 v11, 0x4000, v11
	global_load_dword v134, v11, s[66:67] nt
	v_add_u32_e32 v11, 0x4000, v11
	global_load_dword v135, v11, s[66:67] nt
	v_add_u32_e32 v11, 0x4000, v11
	global_load_dword v136, v11, s[66:67] nt
	v_add_u32_e32 v11, 0x4000, v11
	global_load_dword v137, v11, s[66:67] nt
	v_add_u32_e32 v11, 0x4000, v11
	global_load_dword v138, v11, s[66:67] nt
	v_add_u32_e32 v11, 0x4000, v11
	global_load_dword v139, v11, s[66:67] nt
	s_branch .Lxpfdd19_procA

; #define LAS __attribute__((address_space(3)))
; __device__ __forceinline__ unsigned cvt_pk_bf16(float lo, float hi) { unsigned r; asm volatile("v_cvt_pk_bf16_f32 %0, %1, %2" : "=v"(r) : "v"(lo), "v"(hi)); return r; }
; __device__ __forceinline__ void xpose_item(const float* src, int ld, bf16_t* dst, int K, int k0, LAS float* scr, int lane, const float* gk) {
;     ...
;         for (int i = 0; i < 32; ++i) { const int kk = 2 * i + (lane >> 5); scr[kk * 33 + (lane & 31)] = __builtin_nontemporal_load(src + (size_t)(k0 + kk) * ld + (lane & 31)); }
;     } else {
; #pragma unroll 8
;         for (int i = 0; i < 32; ++i) { const int kk = 2 * i + (lane >> 5); scr[kk * 33 + (lane & 31)] = 0.f; }
;     }
;     const int c = lane & 7;
;     f32x4 g0 = (f32x4){1.f, 1.f, 1.f, 1.f}, g1 = g0;
;     if (gk) { g0 = *(const f32x4*)(gk + k0 + 8 * c); g1 = *(const f32x4*)(gk + k0 + 8 * c + 4); }
;     asm volatile("s_waitcnt lgkmcnt(0)" ::: "memory");
; #pragma unroll
;     for (int j = 0; j < 4; ++j) { const int n = (lane >> 3) + 8 * j; const LAS float* s = scr + (8 * c) * 33 + n;
;         u32x4 o; o.x = cvt_pk_bf16(s[0 * 33] * g0[0], s[1 * 33] * g0[1]); o.y = cvt_pk_bf16(s[2 * 33] * g0[2], s[3 * 33] * g0[3]); o.z = cvt_pk_bf16(s[4 * 33] * g1[0], s[5 * 33] * g1[1]); o.w = cvt_pk_bf16(s[6 * 33] * g1[2], s[7 * 33] * g1[3]);
;         *(u32x4*)(dst + (size_t)n * K + k0 + 8 * c) = o; }
.Lxpfdd19_procA:
	s_lshr_b32 s64, s59, 6
	s_and_b32 s65, s59, 63
	s_mul_i32 s68, s65, 0x58000
	s_lshl_b32 s64, s64, 7
	s_add_i32 s68, s68, s64
	s_add_u32 s64, s62, s68
	s_addc_u32 s65, s63, 0
	s_waitcnt vmcnt(63)
	ds_write_b32 v6, v20 offset:0
	s_waitcnt vmcnt(62)
	ds_write_b32 v6, v21 offset:264
	s_waitcnt vmcnt(61)
	ds_write_b32 v6, v22 offset:528
	s_waitcnt vmcnt(60)
	ds_write_b32 v6, v23 offset:792
	s_waitcnt vmcnt(59)
	ds_write_b32 v6, v24 offset:1056
	s_waitcnt vmcnt(58)
	ds_write_b32 v6, v25 offset:1320
	s_waitcnt vmcnt(57)
	ds_write_b32 v6, v26 offset:1584
	s_waitcnt vmcnt(56)
	ds_write_b32 v6, v27 offset:1848
	s_waitcnt vmcnt(55)
	ds_write_b32 v6, v28 offset:2112
	s_waitcnt vmcnt(54)
	ds_write_b32 v6, v29 offset:2376
	s_waitcnt vmcnt(53)
	ds_write_b32 v6, v30 offset:2640
	s_waitcnt vmcnt(52)
	ds_write_b32 v6, v31 offset:2904
	s_waitcnt vmcnt(51)
	ds_write_b32 v6, v32 offset:3168
	s_waitcnt vmcnt(50)
	ds_write_b32 v6, v33 offset:3432
	s_waitcnt vmcnt(49)
	ds_write_b32 v6, v34 offset:3696
	s_waitcnt vmcnt(48)
	ds_write_b32 v6, v35 offset:3960
	s_waitcnt vmcnt(47)
	ds_write_b32 v6, v36 offset:4224
	s_waitcnt vmcnt(46)
	ds_write_b32 v6, v37 offset:4488
	s_waitcnt vmcnt(45)
	ds_write_b32 v6, v38 offset:4752
	s_waitcnt vmcnt(44)
	ds_write_b32 v6, v39 offset:5016
	s_waitcnt vmcnt(43)
	ds_write_b32 v6, v40 offset:5280
	s_waitcnt vmcnt(42)
	ds_write_b32 v6, v41 offset:5544
	s_waitcnt vmcnt(41)
	ds_write_b32 v6, v42 offset:5808
	s_waitcnt vmcnt(40)
	ds_write_b32 v6, v43 offset:6072
	s_waitcnt vmcnt(39)
	ds_write_b32 v6, v44 offset:6336
	s_waitcnt vmcnt(38)
	ds_write_b32 v6, v45 offset:6600
	s_waitcnt vmcnt(37)
	ds_write_b32 v6, v46 offset:6864
	s_waitcnt vmcnt(36)
	ds_write_b32 v6, v47 offset:7128
	s_waitcnt vmcnt(35)
	ds_write_b32 v6, v48 offset:7392
	s_waitcnt vmcnt(34)
	ds_write_b32 v6, v49 offset:7656
	s_waitcnt vmcnt(33)
	ds_write_b32 v6, v50 offset:7920
	s_waitcnt vmcnt(32)
	ds_write_b32 v6, v51 offset:8184
	s_waitcnt lgkmcnt(0)
	ds_read2_b32 v[60:61], v9 offset0:0 offset1:33
	ds_read2_b32 v[62:63], v9 offset0:66 offset1:99
	ds_read2_b32 v[64:65], v9 offset0:132 offset1:165
	ds_read2_b32 v[66:67], v9 offset0:198 offset1:231
	ds_read2_b32 v[68:69], v9 offset0:8 offset1:41
	ds_read2_b32 v[70:71], v9 offset0:74 offset1:107
	ds_read2_b32 v[72:73], v9 offset0:140 offset1:173
	ds_read2_b32 v[74:75], v9 offset0:206 offset1:239
	ds_read2_b32 v[76:77], v9 offset0:16 offset1:49
	ds_read2_b32 v[78:79], v9 offset0:82 offset1:115
	ds_read2_b32 v[80:81], v9 offset0:148 offset1:181
	ds_read2_b32 v[82:83], v9 offset0:214 offset1:247
	ds_read2_b32 v[84:85], v9 offset0:24 offset1:57
	ds_read2_b32 v[86:87], v9 offset0:90 offset1:123
	ds_read2_b32 v[88:89], v9 offset0:156 offset1:189
	ds_read2_b32 v[90:91], v9 offset0:222 offset1:255
	s_waitcnt lgkmcnt(12)
	v_cvt_pk_bf16_f32 v92, v60, v61
	v_cvt_pk_bf16_f32 v93, v62, v63
	v_cvt_pk_bf16_f32 v94, v64, v65
	v_cvt_pk_bf16_f32 v95, v66, v67
	global_store_dwordx4 v12, v[92:95], s[64:65]
	s_waitcnt lgkmcnt(8)
	v_cvt_pk_bf16_f32 v96, v68, v69
	v_cvt_pk_bf16_f32 v97, v70, v71
	v_cvt_pk_bf16_f32 v98, v72, v73
	v_cvt_pk_bf16_f32 v99, v74, v75
	global_store_dwordx4 v13, v[96:99], s[64:65]
	s_waitcnt lgkmcnt(4)
	v_cvt_pk_bf16_f32 v100, v76, v77
	v_cvt_pk_bf16_f32 v101, v78, v79
	v_cvt_pk_bf16_f32 v102, v80, v81
	v_cvt_pk_bf16_f32 v103, v82, v83
	global_store_dwordx4 v14, v[100:103], s[64:65]
	s_waitcnt lgkmcnt(0)
	v_cvt_pk_bf16_f32 v104, v84, v85
	v_cvt_pk_bf16_f32 v105, v86, v87
	v_cvt_pk_bf16_f32 v106, v88, v89
	v_cvt_pk_bf16_f32 v107, v90, v91
	global_store_dwordx4 v15, v[104:107], s[64:65]
	s_cmpk_lt_i32 s32, 0x1600
	s_cbranch_scc0 .Lxpfdd19_fin
	s_add_i32 s59, s32, 0x80
	s_cmpk_lt_i32 s59, 0x1600
	s_cbranch_scc0 .Lxpfdd19_dumA
	s_lshr_b32 s64, s59, 6
	s_and_b32 s65, s59, 63
	s_mul_i32 s66, s64, 0x80000
	s_lshl_b32 s67, s65, 7
	s_add_i32 s66, s66, s67
	s_add_u32 s66, s60, s66
	s_addc_u32 s67, s61, 0
	v_mov_b32_e32 v11, v5
	global_load_dword v20, v11, s[66:67] nt
	v_add_u32_e32 v11, 0x4000, v11
	global_load_dword v21, v11, s[66:67] nt
	v_add_u32_e32 v11, 0x4000, v11
	global_load_dword v22, v11, s[66:67] nt
	v_add_u32_e32 v11, 0x4000, v11
	global_load_dword v23, v11, s[66:67] nt
	v_add_u32_e32 v11, 0x4000, v11
	global_load_dword v24, v11, s[66:67] nt
	v_add_u32_e32 v11, 0x4000, v11
	global_load_dword v25, v11, s[66:67] nt
	v_add_u32_e32 v11, 0x4000, v11
	global_load_dword v26, v11, s[66:67] nt
	v_add_u32_e32 v11, 0x4000, v11
	global_load_dword v27, v11, s[66:67] nt
	v_add_u32_e32 v11, 0x4000, v11
	global_load_dword v28, v11, s[66:67] nt
	v_add_u32_e32 v11, 0x4000, v11
	global_load_dword v29, v11, s[66:67] nt
	v_add_u32_e32 v11, 0x4000, v11
	global_load_dword v30, v11, s[66:67] nt
	v_add_u32_e32 v11, 0x4000, v11
	global_load_dword v31, v11, s[66:67] nt
	v_add_u32_e32 v11, 0x4000, v11
	global_load_dword v32, v11, s[66:67] nt
	v_add_u32_e32 v11, 0x4000, v11
	global_load_dword v33, v11, s[66:67] nt
	v_add_u32_e32 v11, 0x4000, v11
	global_load_dword v34, v11, s[66:67] nt
	v_add_u32_e32 v11, 0x4000, v11
	global_load_dword v35, v11, s[66:67] nt
	v_add_u32_e32 v11, 0x4000, v11
	global_load_dword v36, v11, s[66:67] nt
	v_add_u32_e32 v11, 0x4000, v11
	global_load_dword v37, v11, s[66:67] nt
	v_add_u32_e32 v11, 0x4000, v11
	global_load_dword v38, v11, s[66:67] nt
	v_add_u32_e32 v11, 0x4000, v11
	global_load_dword v39, v11, s[66:67] nt
	v_add_u32_e32 v11, 0x4000, v11
	global_load_dword v40, v11, s[66:67] nt
	v_add_u32_e32 v11, 0x4000, v11
	global_load_dword v41, v11, s[66:67] nt
	v_add_u32_e32 v11, 0x4000, v11
	global_load_dword v42, v11, s[66:67] nt
	v_add_u32_e32 v11, 0x4000, v11
	global_load_dword v43, v11, s[66:67] nt
	v_add_u32_e32 v11, 0x4000, v11
	global_load_dword v44, v11, s[66:67] nt
	v_add_u32_e32 v11, 0x4000, v11
	global_load_dword v45, v11, s[66:67] nt
	v_add_u32_e32 v11, 0x4000, v11
	global_load_dword v46, v11, s[66:67] nt
	v_add_u32_e32 v11, 0x4000, v11
	global_load_dword v47, v11, s[66:67] nt
	v_add_u32_e32 v11, 0x4000, v11
	global_load_dword v48, v11, s[66:67] nt
	v_add_u32_e32 v11, 0x4000, v11
	global_load_dword v49, v11, s[66:67] nt
	v_add_u32_e32 v11, 0x4000, v11
	global_load_dword v50, v11, s[66:67] nt
	v_add_u32_e32 v11, 0x4000, v11
	global_load_dword v51, v11, s[66:67] nt
	s_branch .Lxpfdd19_procB

; #define LAS __attribute__((address_space(3)))
; __device__ __forceinline__ void xpose_item(const float* src, int ld, bf16_t* dst, int K, int k0, LAS float* scr, int lane, const float* gk) {
;     if (src) {
; #pragma unroll 8
;         for (int i = 0; i < 32; ++i) { const int kk = 2 * i + (lane >> 5); scr[kk * 33 + (lane & 31)] = __builtin_nontemporal_load(src + (size_t)(k0 + kk) * ld + (lane & 31)); }
;     } else {
; #pragma unroll 8
;         for (int i = 0; i < 32; ++i) { const int kk = 2 * i + (lane >> 5); scr[kk * 33 + (lane & 31)] = 0.f; }
;     }
;     const int c = lane & 7;
;     f32x4 g0 = (f32x4){1.f, 1.f, 1.f, 1.f}, g1 = g0;
;     if (gk) { g0 = *(const f32x4*)(gk + k0 + 8 * c); g1 = *(const f32x4*)(gk + k0 + 8 * c + 4); }
;     asm volatile("s_waitcnt lgkmcnt(0)" ::: "memory");
; #pragma unroll
;     for (int j = 0; j < 4; ++j) { const int n = (lane >> 3) + 8 * j; const LAS float* s = scr + (8 * c) * 33 + n;
; __global__ void __launch_bounds__(512) mega(Args a_byval) {
;     ...
;             it = xpose_all(a.in[27] + (size_t)lyr * D * D, nullptr, 2048, 2048, 2048, 2048, 0, (bf16_t*)(ws + (lyr ? WS_W_PG1 : WS_W_PG)), it, NGW, scr, lane, norm_ple_g + lyr * D);
.Lxpfdd19_end:
	s_sub_i32 s59, s59, 0x1600
	s_movk_i32 s33, 0x84
.Lxcd19_done:
	s_cmp_lg_u32 s76, 19
	s_cbranch_scc1 .Lxct19_done
	v_readlane_b32 s59, v255, 5
	s_cmpk_lg_i32 s59, 0x100
	s_cbranch_scc1 .Lxct19_done
	s_cmpk_lt_i32 s94, 0xd0
	s_cbranch_scc1 .Lxct19_done
	s_cmpk_gt_i32 s94, 0xef
	s_cbranch_scc1 .Lxct19_done
	s_sub_i32 s59, s94, 0xd0
	s_lshl_b32 s59, s59, 3
	s_add_i32 s59, s59, s95
	s_mul_i32 s64, s95, 0x2100
	v_and_b32_e32 v2, 31, v200
	v_lshrrev_b32_e32 v3, 5, v200
	v_lshlrev_b32_e32 v4, 2, v2
	v_mul_u32_u24_e32 v6, 0x84, v3
	v_add3_u32 v6, v6, v4, s64
	v_and_b32_e32 v7, 7, v200
	v_lshrrev_b32_e32 v8, 3, v200
	v_mul_u32_u24_e32 v9, 0x420, v7
	v_lshl_add_u32 v9, v8, 2, v9
	v_add_u32_e32 v9, s64, v9
	s_cmpk_ge_i32 s59, 0x800
	s_cbranch_scc1 .Lxppgt19_end
	s_load_dwordx2 s[60:61], s[92:93], 0xd8
	s_load_dwordx2 s[62:63], s[92:93], 0xe8
	s_load_dwordx2 s[64:65], s[92:93], 0x20
	v_mov_b32_e32 v5, 0x2000
	v_mul_u32_u24_e32 v5, v3, v5
	v_add_u32_e32 v5, v5, v4
	v_mov_b32_e32 v10, 0x1000
	v_mul_u32_u24_e32 v10, v8, v10
	v_lshl_add_u32 v12, v7, 4, v10
	v_add_u32_e32 v13, 0x8000, v12
	v_add_u32_e32 v14, 0x10000, v12
	v_add_u32_e32 v15, 0x18000, v12
	s_waitcnt lgkmcnt(0)
	s_add_u32 s60, s60, 0x1000000
	s_addc_u32 s61, s61, 0
	s_add_u32 s62, s62, 0x1a00000
	s_addc_u32 s63, s63, 0
	s_add_u32 s64, s64, 0x2000
	s_addc_u32 s65, s65, 0
	v_lshlrev_b32_e32 v16, 5, v7
	v_mov_b32_e32 v17, v0
	v_lshl_add_u64 v[16:17], s[64:65], 0, v[16:17]
	s_lshr_b32 s64, s59, 6
	s_and_b32 s65, s59, 63
	s_mul_i32 s66, s64, 0x80000
	s_lshl_b32 s67, s65, 7
	s_add_i32 s66, s66, s67
	s_add_u32 s66, s60, s66
	s_addc_u32 s67, s61, 0
	s_lshl_b32 s64, s64, 8
	s_mov_b32 s65, 0
	v_lshl_add_u64 v[18:19], s[64:65], 0, v[16:17]
	global_load_dwordx4 v[52:55], v[18:19], off
	global_load_dwordx4 v[56:59], v[18:19], off offset:16
	v_mov_b32_e32 v11, v5
	global_load_dword v20, v11, s[66:67] nt
	v_add_u32_e32 v11, 0x4000, v11
	global_load_dword v21, v11, s[66:67] nt
	v_add_u32_e32 v11, 0x4000, v11
	global_load_dword v22, v11, s[66:67] nt
	v_add_u32_e32 v11, 0x4000, v11
	global_load_dword v23, v11, s[66:67] nt
	v_add_u32_e32 v11, 0x4000, v11
	global_load_dword v24, v11, s[66:67] nt
	v_add_u32_e32 v11, 0x4000, v11
	global_load_dword v25, v11, s[66:67] nt
	v_add_u32_e32 v11, 0x4000, v11
	global_load_dword v26, v11, s[66:67] nt
	v_add_u32_e32 v11, 0x4000, v11
	global_load_dword v27, v11, s[66:67] nt
	v_add_u32_e32 v11, 0x4000, v11
	global_load_dword v28, v11, s[66:67] nt
	v_add_u32_e32 v11, 0x4000, v11
	global_load_dword v29, v11, s[66:67] nt
	v_add_u32_e32 v11, 0x4000, v11
	global_load_dword v30, v11, s[66:67] nt
	v_add_u32_e32 v11, 0x4000, v11
	global_load_dword v31, v11, s[66:67] nt
	v_add_u32_e32 v11, 0x4000, v11
	global_load_dword v32, v11, s[66:67] nt
	v_add_u32_e32 v11, 0x4000, v11
	global_load_dword v33, v11, s[66:67] nt
	v_add_u32_e32 v11, 0x4000, v11
	global_load_dword v34, v11, s[66:67] nt
	v_add_u32_e32 v11, 0x4000, v11
	global_load_dword v35, v11, s[66:67] nt
	v_add_u32_e32 v11, 0x4000, v11
	global_load_dword v36, v11, s[66:67] nt
	v_add_u32_e32 v11, 0x4000, v11
	global_load_dword v37, v11, s[66:67] nt
	v_add_u32_e32 v11, 0x4000, v11
	global_load_dword v38, v11, s[66:67] nt
	v_add_u32_e32 v11, 0x4000, v11
	global_load_dword v39, v11, s[66:67] nt
	v_add_u32_e32 v11, 0x4000, v11
	global_load_dword v40, v11, s[66:67] nt
	v_add_u32_e32 v11, 0x4000, v11
	global_load_dword v41, v11, s[66:67] nt
	v_add_u32_e32 v11, 0x4000, v11
	global_load_dword v42, v11, s[66:67] nt
	v_add_u32_e32 v11, 0x4000, v11
	global_load_dword v43, v11, s[66:67] nt
	v_add_u32_e32 v11, 0x4000, v11
	global_load_dword v44, v11, s[66:67] nt
	v_add_u32_e32 v11, 0x4000, v11
	global_load_dword v45, v11, s[66:67] nt
	v_add_u32_e32 v11, 0x4000, v11
	global_load_dword v46, v11, s[66:67] nt
	v_add_u32_e32 v11, 0x4000, v11
	global_load_dword v47, v11, s[66:67] nt
	v_add_u32_e32 v11, 0x4000, v11
	global_load_dword v48, v11, s[66:67] nt
	v_add_u32_e32 v11, 0x4000, v11
	global_load_dword v49, v11, s[66:67] nt
	v_add_u32_e32 v11, 0x4000, v11
	global_load_dword v50, v11, s[66:67] nt
	v_add_u32_e32 v11, 0x4000, v11
	global_load_dword v51, v11, s[66:67] nt
.Lxppgt19_loop:
	s_add_i32 s32, s59, 0x100
	s_cmpk_lt_i32 s32, 0x800
	s_cbranch_scc0 .Lxppgt19_dumB
	s_lshr_b32 s64, s32, 6
	s_and_b32 s65, s32, 63
	s_mul_i32 s66, s64, 0x80000
	s_lshl_b32 s67, s65, 7
	s_add_i32 s66, s66, s67
	s_add_u32 s66, s60, s66
	s_addc_u32 s67, s61, 0
	s_lshl_b32 s64, s64, 8
	s_mov_b32 s65, 0
	v_lshl_add_u64 v[18:19], s[64:65], 0, v[16:17]
	global_load_dwordx4 v[160:163], v[18:19], off
	global_load_dwordx4 v[164:167], v[18:19], off offset:16
	v_mov_b32_e32 v11, v5
	global_load_dword v108, v11, s[66:67] nt
	v_add_u32_e32 v11, 0x4000, v11
	global_load_dword v109, v11, s[66:67] nt
	v_add_u32_e32 v11, 0x4000, v11
	global_load_dword v110, v11, s[66:67] nt
	v_add_u32_e32 v11, 0x4000, v11
	global_load_dword v111, v11, s[66:67] nt
	v_add_u32_e32 v11, 0x4000, v11
	global_load_dword v112, v11, s[66:67] nt
	v_add_u32_e32 v11, 0x4000, v11
	global_load_dword v113, v11, s[66:67] nt
	v_add_u32_e32 v11, 0x4000, v11
	global_load_dword v114, v11, s[66:67] nt
	v_add_u32_e32 v11, 0x4000, v11
	global_load_dword v115, v11, s[66:67] nt
	v_add_u32_e32 v11, 0x4000, v11
	global_load_dword v116, v11, s[66:67] nt
	v_add_u32_e32 v11, 0x4000, v11
	global_load_dword v117, v11, s[66:67] nt
	v_add_u32_e32 v11, 0x4000, v11
	global_load_dword v118, v11, s[66:67] nt
	v_add_u32_e32 v11, 0x4000, v11
	global_load_dword v119, v11, s[66:67] nt
	v_add_u32_e32 v11, 0x4000, v11
	global_load_dword v120, v11, s[66:67] nt
	v_add_u32_e32 v11, 0x4000, v11
	global_load_dword v121, v11, s[66:67] nt
	v_add_u32_e32 v11, 0x4000, v11
	global_load_dword v122, v11, s[66:67] nt
	v_add_u32_e32 v11, 0x4000, v11
	global_load_dword v123, v11, s[66:67] nt
	v_add_u32_e32 v11, 0x4000, v11
	global_load_dword v124, v11, s[66:67] nt
	v_add_u32_e32 v11, 0x4000, v11
	global_load_dword v125, v11, s[66:67] nt
	v_add_u32_e32 v11, 0x4000, v11
	global_load_dword v126, v11, s[66:67] nt
	v_add_u32_e32 v11, 0x4000, v11
	global_load_dword v127, v11, s[66:67] nt
	v_add_u32_e32 v11, 0x4000, v11
	global_load_dword v128, v11, s[66:67] nt
	v_add_u32_e32 v11, 0x4000, v11
	global_load_dword v129, v11, s[66:67] nt
	v_add_u32_e32 v11, 0x4000, v11
	global_load_dword v130, v11, s[66:67] nt
	v_add_u32_e32 v11, 0x4000, v11
	global_load_dword v131, v11, s[66:67] nt
	v_add_u32_e32 v11, 0x4000, v11
	global_load_dword v132, v11, s[66:67] nt
	v_add_u32_e32 v11, 0x4000, v11
	global_load_dword v133, v11, s[66:67] nt
	v_add_u32_e32 v11, 0x4000, v11
	global_load_dword v134, v11, s[66:67] nt
	v_add_u32_e32 v11, 0x4000, v11
	global_load_dword v135, v11, s[66:67] nt
	v_add_u32_e32 v11, 0x4000, v11
	global_load_dword v136, v11, s[66:67] nt
	v_add_u32_e32 v11, 0x4000, v11
	global_load_dword v137, v11, s[66:67] nt
	v_add_u32_e32 v11, 0x4000, v11
	global_load_dword v138, v11, s[66:67] nt
	v_add_u32_e32 v11, 0x4000, v11
	global_load_dword v139, v11, s[66:67] nt
	s_branch .Lxppgt19_procA

; #define LAS __attribute__((address_space(3)))
; __device__ __forceinline__ unsigned cvt_pk_bf16(float lo, float hi) { unsigned r; asm volatile("v_cvt_pk_bf16_f32 %0, %1, %2" : "=v"(r) : "v"(lo), "v"(hi)); return r; }
; __device__ __forceinline__ void xpose_item(const float* src, int ld, bf16_t* dst, int K, int k0, LAS float* scr, int lane, const float* gk) {
;     ...
;     const int c = lane & 7;
;     f32x4 g0 = (f32x4){1.f, 1.f, 1.f, 1.f}, g1 = g0;
;     if (gk) { g0 = *(const f32x4*)(gk + k0 + 8 * c); g1 = *(const f32x4*)(gk + k0 + 8 * c + 4); }
;     asm volatile("s_waitcnt lgkmcnt(0)" ::: "memory");
; #pragma unroll
;     for (int j = 0; j < 4; ++j) { const int n = (lane >> 3) + 8 * j; const LAS float* s = scr + (8 * c) * 33 + n;
;         u32x4 o; o.x = cvt_pk_bf16(s[0 * 33] * g0[0], s[1 * 33] * g0[1]); o.y = cvt_pk_bf16(s[2 * 33] * g0[2], s[3 * 33] * g0[3]); o.z = cvt_pk_bf16(s[4 * 33] * g1[0], s[5 * 33] * g1[1]); o.w = cvt_pk_bf16(s[6 * 33] * g1[2], s[7 * 33] * g1[3]);
;         *(u32x4*)(dst + (size_t)n * K + k0 + 8 * c) = o; }
.Lxppgt19_procA:
	s_lshr_b32 s64, s59, 6
	s_and_b32 s65, s59, 63
	s_mul_i32 s68, s65, 0x20000
	s_lshl_b32 s64, s64, 7
	s_add_i32 s68, s68, s64
	s_add_u32 s64, s62, s68
	s_addc_u32 s65, s63, 0
	s_waitcnt vmcnt(63)
	ds_write_b32 v6, v20 offset:0
	s_waitcnt vmcnt(62)
	ds_write_b32 v6, v21 offset:264
	s_waitcnt vmcnt(61)
	ds_write_b32 v6, v22 offset:528
	s_waitcnt vmcnt(60)
	ds_write_b32 v6, v23 offset:792
	s_waitcnt vmcnt(59)
	ds_write_b32 v6, v24 offset:1056
	s_waitcnt vmcnt(58)
	ds_write_b32 v6, v25 offset:1320
	s_waitcnt vmcnt(57)
	ds_write_b32 v6, v26 offset:1584
	s_waitcnt vmcnt(56)
	ds_write_b32 v6, v27 offset:1848
	s_waitcnt vmcnt(55)
	ds_write_b32 v6, v28 offset:2112
	s_waitcnt vmcnt(54)
	ds_write_b32 v6, v29 offset:2376
	s_waitcnt vmcnt(53)
	ds_write_b32 v6, v30 offset:2640
	s_waitcnt vmcnt(52)
	ds_write_b32 v6, v31 offset:2904
	s_waitcnt vmcnt(51)
	ds_write_b32 v6, v32 offset:3168
	s_waitcnt vmcnt(50)
	ds_write_b32 v6, v33 offset:3432
	s_waitcnt vmcnt(49)
	ds_write_b32 v6, v34 offset:3696
	s_waitcnt vmcnt(48)
	ds_write_b32 v6, v35 offset:3960
	s_waitcnt vmcnt(47)
	ds_write_b32 v6, v36 offset:4224
	s_waitcnt vmcnt(46)
	ds_write_b32 v6, v37 offset:4488
	s_waitcnt vmcnt(45)
	ds_write_b32 v6, v38 offset:4752
	s_waitcnt vmcnt(44)
	ds_write_b32 v6, v39 offset:5016
	s_waitcnt vmcnt(43)
	ds_write_b32 v6, v40 offset:5280
	s_waitcnt vmcnt(42)
	ds_write_b32 v6, v41 offset:5544
	s_waitcnt vmcnt(41)
	ds_write_b32 v6, v42 offset:5808
	s_waitcnt vmcnt(40)
	ds_write_b32 v6, v43 offset:6072
	s_waitcnt vmcnt(39)
	ds_write_b32 v6, v44 offset:6336
	s_waitcnt vmcnt(38)
	ds_write_b32 v6, v45 offset:6600
	s_waitcnt vmcnt(37)
	ds_write_b32 v6, v46 offset:6864
	s_waitcnt vmcnt(36)
	ds_write_b32 v6, v47 offset:7128
	s_waitcnt vmcnt(35)
	ds_write_b32 v6, v48 offset:7392
	s_waitcnt vmcnt(34)
	ds_write_b32 v6, v49 offset:7656
	s_waitcnt vmcnt(33)
	ds_write_b32 v6, v50 offset:7920
	s_waitcnt vmcnt(32)
	ds_write_b32 v6, v51 offset:8184
	s_waitcnt lgkmcnt(0)
	ds_read2_b32 v[60:61], v9 offset0:0 offset1:33
	ds_read2_b32 v[62:63], v9 offset0:66 offset1:99
	ds_read2_b32 v[64:65], v9 offset0:132 offset1:165
	ds_read2_b32 v[66:67], v9 offset0:198 offset1:231
	ds_read2_b32 v[68:69], v9 offset0:8 offset1:41
	ds_read2_b32 v[70:71], v9 offset0:74 offset1:107
	ds_read2_b32 v[72:73], v9 offset0:140 offset1:173
	ds_read2_b32 v[74:75], v9 offset0:206 offset1:239
	ds_read2_b32 v[76:77], v9 offset0:16 offset1:49
	ds_read2_b32 v[78:79], v9 offset0:82 offset1:115
	ds_read2_b32 v[80:81], v9 offset0:148 offset1:181
	ds_read2_b32 v[82:83], v9 offset0:214 offset1:247
	ds_read2_b32 v[84:85], v9 offset0:24 offset1:57
	ds_read2_b32 v[86:87], v9 offset0:90 offset1:123
	ds_read2_b32 v[88:89], v9 offset0:156 offset1:189
	ds_read2_b32 v[90:91], v9 offset0:222 offset1:255
	s_waitcnt lgkmcnt(12)
	v_mul_f32_e32 v60, v60, v52
	v_mul_f32_e32 v61, v61, v53
	v_mul_f32_e32 v62, v62, v54
	v_mul_f32_e32 v63, v63, v55
	v_mul_f32_e32 v64, v64, v56
	v_mul_f32_e32 v65, v65, v57
	v_mul_f32_e32 v66, v66, v58
	v_mul_f32_e32 v67, v67, v59
	v_cvt_pk_bf16_f32 v92, v60, v61
	v_cvt_pk_bf16_f32 v93, v62, v63
	v_cvt_pk_bf16_f32 v94, v64, v65
	v_cvt_pk_bf16_f32 v95, v66, v67
	global_store_dwordx4 v12, v[92:95], s[64:65]
	s_waitcnt lgkmcnt(8)
	v_mul_f32_e32 v68, v68, v52
	v_mul_f32_e32 v69, v69, v53
	v_mul_f32_e32 v70, v70, v54
	v_mul_f32_e32 v71, v71, v55
	v_mul_f32_e32 v72, v72, v56
	v_mul_f32_e32 v73, v73, v57
	v_mul_f32_e32 v74, v74, v58
	v_mul_f32_e32 v75, v75, v59
	v_cvt_pk_bf16_f32 v96, v68, v69
	v_cvt_pk_bf16_f32 v97, v70, v71
	v_cvt_pk_bf16_f32 v98, v72, v73
	v_cvt_pk_bf16_f32 v99, v74, v75
	global_store_dwordx4 v13, v[96:99], s[64:65]
	s_waitcnt lgkmcnt(4)
	v_mul_f32_e32 v76, v76, v52
	v_mul_f32_e32 v77, v77, v53
	v_mul_f32_e32 v78, v78, v54
	v_mul_f32_e32 v79, v79, v55
	v_mul_f32_e32 v80, v80, v56
	v_mul_f32_e32 v81, v81, v57
	v_mul_f32_e32 v82, v82, v58
	v_mul_f32_e32 v83, v83, v59
	v_cvt_pk_bf16_f32 v100, v76, v77
	v_cvt_pk_bf16_f32 v101, v78, v79
	v_cvt_pk_bf16_f32 v102, v80, v81
	v_cvt_pk_bf16_f32 v103, v82, v83
	global_store_dwordx4 v14, v[100:103], s[64:65]
	s_waitcnt lgkmcnt(0)
	v_mul_f32_e32 v84, v84, v52
	v_mul_f32_e32 v85, v85, v53
	v_mul_f32_e32 v86, v86, v54
	v_mul_f32_e32 v87, v87, v55
	v_mul_f32_e32 v88, v88, v56
	v_mul_f32_e32 v89, v89, v57
	v_mul_f32_e32 v90, v90, v58
	v_mul_f32_e32 v91, v91, v59
	v_cvt_pk_bf16_f32 v104, v84, v85
	v_cvt_pk_bf16_f32 v105, v86, v87
	v_cvt_pk_bf16_f32 v106, v88, v89
	v_cvt_pk_bf16_f32 v107, v90, v91
	global_store_dwordx4 v15, v[104:107], s[64:65]
	s_cmpk_lt_i32 s32, 0x800
	s_cbranch_scc0 .Lxppgt19_fin
; __device__ __forceinline__ void xpose_item(const float* src, int ld, bf16_t* dst, int K, int k0, LAS float* scr, int lane, const float* gk) {
;     if (src) {
; #pragma unroll 8
;         for (int i = 0; i < 32; ++i) { const int kk = 2 * i + (lane >> 5); scr[kk * 33 + (lane & 31)] = __builtin_nontemporal_load(src + (size_t)(k0 + kk) * ld + (lane & 31)); }
	s_add_i32 s59, s32, 0x100
	s_cmpk_lt_i32 s59, 0x800
	s_cbranch_scc0 .Lxppgt19_dumA
	s_lshr_b32 s64, s59, 6
	s_and_b32 s65, s59, 63
	s_mul_i32 s66, s64, 0x80000
	s_lshl_b32 s67, s65, 7
	s_add_i32 s66, s66, s67
	s_add_u32 s66, s60, s66
	s_addc_u32 s67, s61, 0
	s_lshl_b32 s64, s64, 8
	s_mov_b32 s65, 0
	v_lshl_add_u64 v[18:19], s[64:65], 0, v[16:17]
	global_load_dwordx4 v[52:55], v[18:19], off
	global_load_dwordx4 v[56:59], v[18:19], off offset:16
	v_mov_b32_e32 v11, v5
	global_load_dword v20, v11, s[66:67] nt
	v_add_u32_e32 v11, 0x4000, v11
	global_load_dword v21, v11, s[66:67] nt
	v_add_u32_e32 v11, 0x4000, v11
	global_load_dword v22, v11, s[66:67] nt
	v_add_u32_e32 v11, 0x4000, v11
	global_load_dword v23, v11, s[66:67] nt
	v_add_u32_e32 v11, 0x4000, v11
	global_load_dword v24, v11, s[66:67] nt
	v_add_u32_e32 v11, 0x4000, v11
	global_load_dword v25, v11, s[66:67] nt
	v_add_u32_e32 v11, 0x4000, v11
	global_load_dword v26, v11, s[66:67] nt
	v_add_u32_e32 v11, 0x4000, v11
	global_load_dword v27, v11, s[66:67] nt
	v_add_u32_e32 v11, 0x4000, v11
	global_load_dword v28, v11, s[66:67] nt
	v_add_u32_e32 v11, 0x4000, v11
	global_load_dword v29, v11, s[66:67] nt
	v_add_u32_e32 v11, 0x4000, v11
	global_load_dword v30, v11, s[66:67] nt
	v_add_u32_e32 v11, 0x4000, v11
	global_load_dword v31, v11, s[66:67] nt
	v_add_u32_e32 v11, 0x4000, v11
	global_load_dword v32, v11, s[66:67] nt
	v_add_u32_e32 v11, 0x4000, v11
	global_load_dword v33, v11, s[66:67] nt
	v_add_u32_e32 v11, 0x4000, v11
	global_load_dword v34, v11, s[66:67] nt
	v_add_u32_e32 v11, 0x4000, v11
	global_load_dword v35, v11, s[66:67] nt
	v_add_u32_e32 v11, 0x4000, v11
	global_load_dword v36, v11, s[66:67] nt
	v_add_u32_e32 v11, 0x4000, v11
	global_load_dword v37, v11, s[66:67] nt
	v_add_u32_e32 v11, 0x4000, v11
	global_load_dword v38, v11, s[66:67] nt
	v_add_u32_e32 v11, 0x4000, v11
	global_load_dword v39, v11, s[66:67] nt
	v_add_u32_e32 v11, 0x4000, v11
	global_load_dword v40, v11, s[66:67] nt
	v_add_u32_e32 v11, 0x4000, v11
	global_load_dword v41, v11, s[66:67] nt
	v_add_u32_e32 v11, 0x4000, v11
	global_load_dword v42, v11, s[66:67] nt
	v_add_u32_e32 v11, 0x4000, v11
	global_load_dword v43, v11, s[66:67] nt
	v_add_u32_e32 v11, 0x4000, v11
	global_load_dword v44, v11, s[66:67] nt
	v_add_u32_e32 v11, 0x4000, v11
	global_load_dword v45, v11, s[66:67] nt
	v_add_u32_e32 v11, 0x4000, v11
	global_load_dword v46, v11, s[66:67] nt
	v_add_u32_e32 v11, 0x4000, v11
	global_load_dword v47, v11, s[66:67] nt
	v_add_u32_e32 v11, 0x4000, v11
	global_load_dword v48, v11, s[66:67] nt
	v_add_u32_e32 v11, 0x4000, v11
	global_load_dword v49, v11, s[66:67] nt
	v_add_u32_e32 v11, 0x4000, v11
	global_load_dword v50, v11, s[66:67] nt
	v_add_u32_e32 v11, 0x4000, v11
	global_load_dword v51, v11, s[66:67] nt
	s_branch .Lxppgt19_procB

; __device__ __forceinline__ void xpose_item(const float* src, int ld, bf16_t* dst, int K, int k0, LAS float* scr, int lane, const float* gk) {
;     if (src) {
; #pragma unroll 8
;         for (int i = 0; i < 32; ++i) { const int kk = 2 * i + (lane >> 5); scr[kk * 33 + (lane & 31)] = __builtin_nontemporal_load(src + (size_t)(k0 + kk) * ld + (lane & 31)); }
.Lxpppt19_loop:
	s_add_i32 s32, s59, 0x100
	s_cmpk_lt_i32 s32, 0x100
	s_cbranch_scc0 .Lxpppt19_dumB
	s_lshr_b32 s64, s32, 6
	s_and_b32 s65, s32, 63
	s_mul_i32 s66, s64, 0x80000
	s_lshl_b32 s67, s65, 7
	s_add_i32 s66, s66, s67
	s_add_u32 s66, s60, s66
	s_addc_u32 s67, s61, 0
	v_mov_b32_e32 v11, v5
	global_load_dword v108, v11, s[66:67] nt
	v_add_u32_e32 v11, 0x4000, v11
	global_load_dword v109, v11, s[66:67] nt
	v_add_u32_e32 v11, 0x4000, v11
	global_load_dword v110, v11, s[66:67] nt
	v_add_u32_e32 v11, 0x4000, v11
	global_load_dword v111, v11, s[66:67] nt
	v_add_u32_e32 v11, 0x4000, v11
	global_load_dword v112, v11, s[66:67] nt
	v_add_u32_e32 v11, 0x4000, v11
	global_load_dword v113, v11, s[66:67] nt
	v_add_u32_e32 v11, 0x4000, v11
	global_load_dword v114, v11, s[66:67] nt
	v_add_u32_e32 v11, 0x4000, v11
	global_load_dword v115, v11, s[66:67] nt
	v_add_u32_e32 v11, 0x4000, v11
	global_load_dword v116, v11, s[66:67] nt
	v_add_u32_e32 v11, 0x4000, v11
	global_load_dword v117, v11, s[66:67] nt
	v_add_u32_e32 v11, 0x4000, v11
	global_load_dword v118, v11, s[66:67] nt
	v_add_u32_e32 v11, 0x4000, v11
	global_load_dword v119, v11, s[66:67] nt
	v_add_u32_e32 v11, 0x4000, v11
	global_load_dword v120, v11, s[66:67] nt
	v_add_u32_e32 v11, 0x4000, v11
	global_load_dword v121, v11, s[66:67] nt
	v_add_u32_e32 v11, 0x4000, v11
	global_load_dword v122, v11, s[66:67] nt
	v_add_u32_e32 v11, 0x4000, v11
	global_load_dword v123, v11, s[66:67] nt
	v_add_u32_e32 v11, 0x4000, v11
	global_load_dword v124, v11, s[66:67] nt
	v_add_u32_e32 v11, 0x4000, v11
	global_load_dword v125, v11, s[66:67] nt
	v_add_u32_e32 v11, 0x4000, v11
	global_load_dword v126, v11, s[66:67] nt
	v_add_u32_e32 v11, 0x4000, v11
	global_load_dword v127, v11, s[66:67] nt
	v_add_u32_e32 v11, 0x4000, v11
	global_load_dword v128, v11, s[66:67] nt
	v_add_u32_e32 v11, 0x4000, v11
	global_load_dword v129, v11, s[66:67] nt
	v_add_u32_e32 v11, 0x4000, v11
	global_load_dword v130, v11, s[66:67] nt
	v_add_u32_e32 v11, 0x4000, v11
	global_load_dword v131, v11, s[66:67] nt
	v_add_u32_e32 v11, 0x4000, v11
	global_load_dword v132, v11, s[66:67] nt
	v_add_u32_e32 v11, 0x4000, v11
	global_load_dword v133, v11, s[66:67] nt
	v_add_u32_e32 v11, 0x4000, v11
	global_load_dword v134, v11, s[66:67] nt
	v_add_u32_e32 v11, 0x4000, v11
	global_load_dword v135, v11, s[66:67] nt
	v_add_u32_e32 v11, 0x4000, v11
	global_load_dword v136, v11, s[66:67] nt
	v_add_u32_e32 v11, 0x4000, v11
	global_load_dword v137, v11, s[66:67] nt
	v_add_u32_e32 v11, 0x4000, v11
	global_load_dword v138, v11, s[66:67] nt
	v_add_u32_e32 v11, 0x4000, v11
	global_load_dword v139, v11, s[66:67] nt
	s_branch .Lxpppt19_procA

; #define LAS __attribute__((address_space(3)))
; __device__ __forceinline__ unsigned cvt_pk_bf16(float lo, float hi) { unsigned r; asm volatile("v_cvt_pk_bf16_f32 %0, %1, %2" : "=v"(r) : "v"(lo), "v"(hi)); return r; }
; __device__ __forceinline__ void xpose_item(const float* src, int ld, bf16_t* dst, int K, int k0, LAS float* scr, int lane, const float* gk) {
;     ...
;         for (int i = 0; i < 32; ++i) { const int kk = 2 * i + (lane >> 5); scr[kk * 33 + (lane & 31)] = __builtin_nontemporal_load(src + (size_t)(k0 + kk) * ld + (lane & 31)); }
;     } else {
; #pragma unroll 8
;         for (int i = 0; i < 32; ++i) { const int kk = 2 * i + (lane >> 5); scr[kk * 33 + (lane & 31)] = 0.f; }
;     }
;     const int c = lane & 7;
;     f32x4 g0 = (f32x4){1.f, 1.f, 1.f, 1.f}, g1 = g0;
;     if (gk) { g0 = *(const f32x4*)(gk + k0 + 8 * c); g1 = *(const f32x4*)(gk + k0 + 8 * c + 4); }
;     asm volatile("s_waitcnt lgkmcnt(0)" ::: "memory");
; #pragma unroll
;     for (int j = 0; j < 4; ++j) { const int n = (lane >> 3) + 8 * j; const LAS float* s = scr + (8 * c) * 33 + n;
;         u32x4 o; o.x = cvt_pk_bf16(s[0 * 33] * g0[0], s[1 * 33] * g0[1]); o.y = cvt_pk_bf16(s[2 * 33] * g0[2], s[3 * 33] * g0[3]); o.z = cvt_pk_bf16(s[4 * 33] * g1[0], s[5 * 33] * g1[1]); o.w = cvt_pk_bf16(s[6 * 33] * g1[2], s[7 * 33] * g1[3]);
;         *(u32x4*)(dst + (size_t)n * K + k0 + 8 * c) = o; }
.Lxpppt19_procA:
	s_lshr_b32 s64, s59, 6
	s_and_b32 s65, s59, 63
	s_mul_i32 s68, s65, 0x4000
	s_lshl_b32 s64, s64, 7
	s_add_i32 s68, s68, s64
	s_add_u32 s64, s62, s68
	s_addc_u32 s65, s63, 0
	s_waitcnt vmcnt(63)
	ds_write_b32 v6, v20 offset:0
	s_waitcnt vmcnt(62)
	ds_write_b32 v6, v21 offset:264
	s_waitcnt vmcnt(61)
	ds_write_b32 v6, v22 offset:528
	s_waitcnt vmcnt(60)
	ds_write_b32 v6, v23 offset:792
	s_waitcnt vmcnt(59)
	ds_write_b32 v6, v24 offset:1056
	s_waitcnt vmcnt(58)
	ds_write_b32 v6, v25 offset:1320
	s_waitcnt vmcnt(57)
	ds_write_b32 v6, v26 offset:1584
	s_waitcnt vmcnt(56)
	ds_write_b32 v6, v27 offset:1848
	s_waitcnt vmcnt(55)
	ds_write_b32 v6, v28 offset:2112
	s_waitcnt vmcnt(54)
	ds_write_b32 v6, v29 offset:2376
	s_waitcnt vmcnt(53)
	ds_write_b32 v6, v30 offset:2640
	s_waitcnt vmcnt(52)
	ds_write_b32 v6, v31 offset:2904
	s_waitcnt vmcnt(51)
	ds_write_b32 v6, v32 offset:3168
	s_waitcnt vmcnt(50)
	ds_write_b32 v6, v33 offset:3432
	s_waitcnt vmcnt(49)
	ds_write_b32 v6, v34 offset:3696
	s_waitcnt vmcnt(48)
	ds_write_b32 v6, v35 offset:3960
	s_waitcnt vmcnt(47)
	ds_write_b32 v6, v36 offset:4224
	s_waitcnt vmcnt(46)
	ds_write_b32 v6, v37 offset:4488
	s_waitcnt vmcnt(45)
	ds_write_b32 v6, v38 offset:4752
	s_waitcnt vmcnt(44)
	ds_write_b32 v6, v39 offset:5016
	s_waitcnt vmcnt(43)
	ds_write_b32 v6, v40 offset:5280
	s_waitcnt vmcnt(42)
	ds_write_b32 v6, v41 offset:5544
	s_waitcnt vmcnt(41)
	ds_write_b32 v6, v42 offset:5808
	s_waitcnt vmcnt(40)
	ds_write_b32 v6, v43 offset:6072
	s_waitcnt vmcnt(39)
	ds_write_b32 v6, v44 offset:6336
	s_waitcnt vmcnt(38)
	ds_write_b32 v6, v45 offset:6600
	s_waitcnt vmcnt(37)
	ds_write_b32 v6, v46 offset:6864
	s_waitcnt vmcnt(36)
	ds_write_b32 v6, v47 offset:7128
	s_waitcnt vmcnt(35)
	ds_write_b32 v6, v48 offset:7392
	s_waitcnt vmcnt(34)
	ds_write_b32 v6, v49 offset:7656
	s_waitcnt vmcnt(33)
	ds_write_b32 v6, v50 offset:7920
	s_waitcnt vmcnt(32)
	ds_write_b32 v6, v51 offset:8184
	s_waitcnt lgkmcnt(0)
	ds_read2_b32 v[60:61], v9 offset0:0 offset1:33
	ds_read2_b32 v[62:63], v9 offset0:66 offset1:99
	ds_read2_b32 v[64:65], v9 offset0:132 offset1:165
	ds_read2_b32 v[66:67], v9 offset0:198 offset1:231
	ds_read2_b32 v[68:69], v9 offset0:8 offset1:41
	ds_read2_b32 v[70:71], v9 offset0:74 offset1:107
	ds_read2_b32 v[72:73], v9 offset0:140 offset1:173
	ds_read2_b32 v[74:75], v9 offset0:206 offset1:239
	ds_read2_b32 v[76:77], v9 offset0:16 offset1:49
	ds_read2_b32 v[78:79], v9 offset0:82 offset1:115
	ds_read2_b32 v[80:81], v9 offset0:148 offset1:181
	ds_read2_b32 v[82:83], v9 offset0:214 offset1:247
	ds_read2_b32 v[84:85], v9 offset0:24 offset1:57
	ds_read2_b32 v[86:87], v9 offset0:90 offset1:123
	ds_read2_b32 v[88:89], v9 offset0:156 offset1:189
	ds_read2_b32 v[90:91], v9 offset0:222 offset1:255
	s_waitcnt lgkmcnt(12)
	v_cvt_pk_bf16_f32 v92, v60, v61
	v_cvt_pk_bf16_f32 v93, v62, v63
	v_cvt_pk_bf16_f32 v94, v64, v65
	v_cvt_pk_bf16_f32 v95, v66, v67
	global_store_dwordx4 v12, v[92:95], s[64:65]
	s_waitcnt lgkmcnt(8)
	v_cvt_pk_bf16_f32 v96, v68, v69
	v_cvt_pk_bf16_f32 v97, v70, v71
	v_cvt_pk_bf16_f32 v98, v72, v73
	v_cvt_pk_bf16_f32 v99, v74, v75
	global_store_dwordx4 v13, v[96:99], s[64:65]
	s_waitcnt lgkmcnt(4)
	v_cvt_pk_bf16_f32 v100, v76, v77
	v_cvt_pk_bf16_f32 v101, v78, v79
	v_cvt_pk_bf16_f32 v102, v80, v81
	v_cvt_pk_bf16_f32 v103, v82, v83
	global_store_dwordx4 v14, v[100:103], s[64:65]
	s_waitcnt lgkmcnt(0)
	v_cvt_pk_bf16_f32 v104, v84, v85
	v_cvt_pk_bf16_f32 v105, v86, v87
	v_cvt_pk_bf16_f32 v106, v88, v89
	v_cvt_pk_bf16_f32 v107, v90, v91
	global_store_dwordx4 v15, v[104:107], s[64:65]
	s_cmpk_lt_i32 s32, 0x100
	s_cbranch_scc0 .Lxpppt19_fin
	s_add_i32 s59, s32, 0x100
	s_cmpk_lt_i32 s59, 0x100
	s_cbranch_scc0 .Lxpppt19_dumA
	s_lshr_b32 s64, s59, 6
	s_and_b32 s65, s59, 63
	s_mul_i32 s66, s64, 0x80000
	s_lshl_b32 s67, s65, 7
	s_add_i32 s66, s66, s67
	s_add_u32 s66, s60, s66
	s_addc_u32 s67, s61, 0
	v_mov_b32_e32 v11, v5
	global_load_dword v20, v11, s[66:67] nt
	v_add_u32_e32 v11, 0x4000, v11
	global_load_dword v21, v11, s[66:67] nt
	v_add_u32_e32 v11, 0x4000, v11
	global_load_dword v22, v11, s[66:67] nt
	v_add_u32_e32 v11, 0x4000, v11
	global_load_dword v23, v11, s[66:67] nt
	v_add_u32_e32 v11, 0x4000, v11
	global_load_dword v24, v11, s[66:67] nt
	v_add_u32_e32 v11, 0x4000, v11
	global_load_dword v25, v11, s[66:67] nt
	v_add_u32_e32 v11, 0x4000, v11
	global_load_dword v26, v11, s[66:67] nt
	v_add_u32_e32 v11, 0x4000, v11
	global_load_dword v27, v11, s[66:67] nt
	v_add_u32_e32 v11, 0x4000, v11
	global_load_dword v28, v11, s[66:67] nt
	v_add_u32_e32 v11, 0x4000, v11
	global_load_dword v29, v11, s[66:67] nt
	v_add_u32_e32 v11, 0x4000, v11
	global_load_dword v30, v11, s[66:67] nt
	v_add_u32_e32 v11, 0x4000, v11
	global_load_dword v31, v11, s[66:67] nt
	v_add_u32_e32 v11, 0x4000, v11
	global_load_dword v32, v11, s[66:67] nt
	v_add_u32_e32 v11, 0x4000, v11
	global_load_dword v33, v11, s[66:67] nt
	v_add_u32_e32 v11, 0x4000, v11
	global_load_dword v34, v11, s[66:67] nt
	v_add_u32_e32 v11, 0x4000, v11
	global_load_dword v35, v11, s[66:67] nt
	v_add_u32_e32 v11, 0x4000, v11
	global_load_dword v36, v11, s[66:67] nt
	v_add_u32_e32 v11, 0x4000, v11
	global_load_dword v37, v11, s[66:67] nt
	v_add_u32_e32 v11, 0x4000, v11
	global_load_dword v38, v11, s[66:67] nt
	v_add_u32_e32 v11, 0x4000, v11
	global_load_dword v39, v11, s[66:67] nt
	v_add_u32_e32 v11, 0x4000, v11
	global_load_dword v40, v11, s[66:67] nt
	v_add_u32_e32 v11, 0x4000, v11
	global_load_dword v41, v11, s[66:67] nt
	v_add_u32_e32 v11, 0x4000, v11
	global_load_dword v42, v11, s[66:67] nt
	v_add_u32_e32 v11, 0x4000, v11
	global_load_dword v43, v11, s[66:67] nt
	v_add_u32_e32 v11, 0x4000, v11
	global_load_dword v44, v11, s[66:67] nt
	v_add_u32_e32 v11, 0x4000, v11
	global_load_dword v45, v11, s[66:67] nt
	v_add_u32_e32 v11, 0x4000, v11
	global_load_dword v46, v11, s[66:67] nt
	v_add_u32_e32 v11, 0x4000, v11
	global_load_dword v47, v11, s[66:67] nt
	v_add_u32_e32 v11, 0x4000, v11
	global_load_dword v48, v11, s[66:67] nt
	v_add_u32_e32 v11, 0x4000, v11
	global_load_dword v49, v11, s[66:67] nt
	v_add_u32_e32 v11, 0x4000, v11
	global_load_dword v50, v11, s[66:67] nt
	v_add_u32_e32 v11, 0x4000, v11
	global_load_dword v51, v11, s[66:67] nt
	s_branch .Lxpppt19_procB

; #define LAS __attribute__((address_space(3)))
; __device__ __forceinline__ unsigned xb_xcc_id() { return (unsigned)__builtin_amdgcn_s_getreg((3 << 11) | 20) & 0xFu; }
; __device__ __forceinline__ void xpose_item(const float* src, int ld, bf16_t* dst, int K, int k0, LAS float* scr, int lane, const float* gk) {
;     ...
;     asm volatile("s_waitcnt lgkmcnt(0)" ::: "memory");
; }
; __global__ void __launch_bounds__(512) mega(Args a_byval) {
;     ...
;         if (rep + 1 < reps) continue;
;         if (ph + 1 < ph_hi) { if (ph_hi > 64) grid.sync();   else { XcdBarrier xbar; xbar.bar = (unsigned*)(ws + WS_BAR); xbar.x = xb_xcc_id(); xbar.st = (volatile LAS unsigned*)((LAS unsigned char*)lds_raw + 135168); xcd_barrier(xbar); } }
.Lxpppt19_end:
	s_sub_i32 s59, s59, 0x100
	s_movk_i32 s33, 0x84
.Lxct19_done:
	s_load_dwordx2 s[38:39], s[92:93], 0xe8
	s_mov_b32 s18, 0x16c02000
	s_mov_b32 s19, 0x16c04000
	s_mov_b32 s20, 0x16c06000
	s_mov_b32 s21, 0x16c07000
	s_mov_b32 s22, 0x1ac07000
	s_mov_b32 s23, 0x10c03000
